# GEMM k-loop heads aligned to 64 B (.p2align 6), on top of v48
# baseline (speedup 1.0000x reference)
;     __device__ __forceinline__ const char* pa(const Unit& u) const { return (const char*)(A + (size_t)u.pm * a_tile_stride + (size_t)((u.pn >> a_group_shift) * a_group_cols)); }
;     __device__ __forceinline__ const char* pb(const Unit& u) const { return (const char*)(Bt + (size_t)u.pn * b_tile_stride); }
;     __device__ __forceinline__ const char* pa(const Unit& u) const { return (const char*)(A + (size_t)u.pm * a_tile_stride + (size_t)u.pn * 512); }
; template <class PT, class Epi>
; __device__ __forceinline__ void gemm_phase_once(LAS unsigned char* lds, const PT& S, const Epi& E, bool epi_on) {
;     ...
;         const bool has_next = S.next(ui + 1, nxt);
;         const char* nA = has_next ? S.pa(nxt) : cA; const char* nB = has_next ? S.pb(nxt) : cB;
;         for (int t = 0; t < nt; t += 2) {
;             const bool last = (t == nt - 2);
;             const char* a1 = cA + (size_t)(t + 1) * kstep;
;             const char* a2 = last ? nA : cA + (size_t)(t + 2) * kstep; const char* b2 = last ? nB : cB + (size_t)(t + 2) * kstep;
;             const char* a3 = a2 + kstep; const char* b3 = b2 + kstep;
;     ...
; #pragma unroll
;         for (int a = 0; a < 2; ++a)
; #pragma unroll
;             for (int b = 0; b < 2; ++b)
; #pragma unroll
;                 for (int m = 0; m < 4; ++m)
; #pragma unroll
;                     for (int n = 0; n < 2; ++n) acc[a][b][m][n] = (f32x4){0.f, 0.f, 0.f, 0.f};
.LBB0_327:
	s_ashr_i32 s7, s6, 31
	s_xor_b64 s[14:15], s[24:25], -1
	s_lshl_b64 s[12:13], s[6:7], 20
	s_add_u32 s12, s72, s12
	s_addc_u32 s13, s73, s13
	s_and_b64 s[16:17], s[24:25], exec
	s_cselect_b32 s7, s13, s21
	s_cselect_b32 s41, s12, s20
	s_ashr_i32 s11, s10, 31
	s_lshl_b64 s[16:17], s[10:11], 20
	v_readlane_b32 s42, v254, 5
	v_readlane_b32 s43, v254, 6
	s_add_u32 s16, s42, s16
	s_addc_u32 s17, s43, s17
	s_and_b64 s[24:25], s[24:25], exec
	s_cselect_b32 s11, s17, s23
	s_cselect_b32 s42, s16, s22
	s_add_u32 s20, s20, 0x80080
	s_addc_u32 s21, s21, 0
	s_add_u32 s43, s22, 0x100
	v_mov_b32_e32 v2, 0
	v_mov_b32_e32 v3, 0
	v_mov_b32_e32 v4, 0
	v_mov_b32_e32 v5, 0
	s_nop 1
	v_mfma_f32_16x16x32_bf16 v[6:9], v[2:5], v[2:5], 0
	v_mfma_f32_16x16x32_bf16 v[10:13], v[2:5], v[2:5], 0
	v_mfma_f32_16x16x32_bf16 v[14:17], v[2:5], v[2:5], 0
	v_mfma_f32_32x32x16_bf16 v[18:33], v[2:5], v[2:5], 0
	v_mfma_f32_32x32x16_bf16 v[34:49], v[2:5], v[2:5], 0
	v_mfma_f32_32x32x16_bf16 v[50:65], v[2:5], v[2:5], 0
	v_mfma_f32_32x32x16_bf16 v[66:81], v[2:5], v[2:5], 0
	v_mfma_f32_32x32x16_bf16 v[82:97], v[2:5], v[2:5], 0
	v_mfma_f32_32x32x16_bf16 v[98:113], v[2:5], v[2:5], 0
	v_mfma_f32_32x32x16_bf16 v[114:129], v[2:5], v[2:5], 0
	s_addc_u32 s44, s23, 0
	s_mov_b32 s45, -2
	.p2align 6

;     __device__ __forceinline__ const char* pa(const Unit& u) const { return (const char*)(A + (size_t)u.pm * a_tile_stride + (size_t)((u.pn >> a_group_shift) * a_group_cols)); }
;     __device__ __forceinline__ const char* pb(const Unit& u) const { return (const char*)(Bt + (size_t)u.pn * b_tile_stride); }
;     __device__ __forceinline__ const char* pa(const Unit& u) const { return (const char*)(A + (size_t)u.pm * a_tile_stride + (size_t)u.pn * 512); }
; template <class PT, class Epi>
; __device__ __forceinline__ void gemm_phase_once(LAS unsigned char* lds, const PT& S, const Epi& E, bool epi_on) {
;     ...
;         const bool has_next = S.next(ui + 1, nxt);
;         const char* nA = has_next ? S.pa(nxt) : cA; const char* nB = has_next ? S.pb(nxt) : cB;
;         for (int t = 0; t < nt; t += 2) {
;             const bool last = (t == nt - 2);
;             const char* a1 = cA + (size_t)(t + 1) * kstep;
;             const char* a2 = last ? nA : cA + (size_t)(t + 2) * kstep; const char* b2 = last ? nB : cB + (size_t)(t + 2) * kstep;
;             const char* a3 = a2 + kstep; const char* b3 = b2 + kstep;
;     ...
; #pragma unroll
;         for (int a = 0; a < 2; ++a)
; #pragma unroll
;             for (int b = 0; b < 2; ++b)
; #pragma unroll
;                 for (int m = 0; m < 4; ++m)
; #pragma unroll
;                     for (int n = 0; n < 2; ++n) acc[a][b][m][n] = (f32x4){0.f, 0.f, 0.f, 0.f};
.LBB0_622:
	s_ashr_i32 s13, s12, 31
	s_lshl_b64 s[16:17], s[12:13], 21
	s_add_u32 s16, s92, s16
	s_addc_u32 s17, s93, s17
	s_and_b64 s[6:7], s[6:7], exec
	s_cselect_b32 s13, s17, s19
	s_cselect_b32 s38, s16, s18
	s_add_u32 s6, s20, 0x180080
	s_addc_u32 s7, s21, 0
	s_add_u32 s39, s18, 0x100
	v_mov_b32_e32 v2, 0
	v_mov_b32_e32 v3, 0
	v_mov_b32_e32 v4, 0
	v_mov_b32_e32 v5, 0
	s_nop 1
	v_mfma_f32_16x16x32_bf16 v[6:9], v[2:5], v[2:5], 0
	v_mfma_f32_16x16x32_bf16 v[10:13], v[2:5], v[2:5], 0
	v_mfma_f32_16x16x32_bf16 v[14:17], v[2:5], v[2:5], 0
	v_mfma_f32_32x32x16_bf16 v[18:33], v[2:5], v[2:5], 0
	v_mfma_f32_32x32x16_bf16 v[34:49], v[2:5], v[2:5], 0
	v_mfma_f32_32x32x16_bf16 v[50:65], v[2:5], v[2:5], 0
	v_mfma_f32_32x32x16_bf16 v[66:81], v[2:5], v[2:5], 0
	v_mfma_f32_32x32x16_bf16 v[82:97], v[2:5], v[2:5], 0
	v_mfma_f32_32x32x16_bf16 v[98:113], v[2:5], v[2:5], 0
	v_mfma_f32_32x32x16_bf16 v[114:129], v[2:5], v[2:5], 0
	s_addc_u32 s40, s19, 0
	s_mov_b32 s41, -2
	.p2align 6

;     __device__ __forceinline__ const char* pa(const Unit& u) const { return (const char*)(A + (size_t)u.pm * a_tile_stride + (size_t)((u.pn >> a_group_shift) * a_group_cols)); }
;     __device__ __forceinline__ const char* pb(const Unit& u) const { return (const char*)(Bt + (size_t)u.pn * b_tile_stride); }
;     __device__ __forceinline__ const char* pa(const Unit& u) const { return (const char*)(A + (size_t)u.pm * a_tile_stride + (size_t)u.pn * 512); }
; template <class PT, class Epi>
; __device__ __forceinline__ void gemm_phase_once(LAS unsigned char* lds, const PT& S, const Epi& E, bool epi_on) {
;     ...
;         const bool has_next = S.next(ui + 1, nxt);
;         const char* nA = has_next ? S.pa(nxt) : cA; const char* nB = has_next ? S.pb(nxt) : cB;
;         for (int t = 0; t < nt; t += 2) {
;             const bool last = (t == nt - 2);
;             const char* a1 = cA + (size_t)(t + 1) * kstep;
;             const char* a2 = last ? nA : cA + (size_t)(t + 2) * kstep; const char* b2 = last ? nB : cB + (size_t)(t + 2) * kstep;
;             const char* a3 = a2 + kstep; const char* b3 = b2 + kstep;
;     ...
; #pragma unroll
;         for (int a = 0; a < 2; ++a)
; #pragma unroll
;             for (int b = 0; b < 2; ++b)
; #pragma unroll
;                 for (int m = 0; m < 4; ++m)
; #pragma unroll
;                     for (int n = 0; n < 2; ++n) acc[a][b][m][n] = (f32x4){0.f, 0.f, 0.f, 0.f};
.LBB0_756:
	s_ashr_i32 s11, s10, 31
	v_cmp_lt_i64_e32 vcc, s[12:13], v[142:143]
	s_lshl_b64 s[12:13], s[10:11], 20
	s_add_u32 s12, s72, s12
	s_addc_u32 s13, s73, s13
	s_and_b64 s[14:15], vcc, exec
	s_cselect_b32 s11, s13, s19
	s_cselect_b32 s39, s12, s18
	s_ashr_i32 s9, s8, 31
	s_lshl_b64 s[14:15], s[8:9], 20
	s_add_u32 s14, s84, s14
	s_addc_u32 s15, s85, s15
	s_and_b64 s[22:23], vcc, exec
	s_cselect_b32 s9, s15, s21
	s_cselect_b32 s40, s14, s20
	s_add_u32 s18, s18, 0x80080
	s_addc_u32 s19, s19, 0
	s_add_u32 s41, s20, 0x100
	v_mov_b32_e32 v2, 0
	v_mov_b32_e32 v3, 0
	v_mov_b32_e32 v4, 0
	v_mov_b32_e32 v5, 0
	s_nop 1
	v_mfma_f32_16x16x32_bf16 v[6:9], v[2:5], v[2:5], 0
	v_mfma_f32_16x16x32_bf16 v[10:13], v[2:5], v[2:5], 0
	v_mfma_f32_16x16x32_bf16 v[14:17], v[2:5], v[2:5], 0
	v_mfma_f32_32x32x16_bf16 v[18:33], v[2:5], v[2:5], 0
	v_mfma_f32_32x32x16_bf16 v[34:49], v[2:5], v[2:5], 0
	v_mfma_f32_32x32x16_bf16 v[50:65], v[2:5], v[2:5], 0
	v_mfma_f32_32x32x16_bf16 v[66:81], v[2:5], v[2:5], 0
	v_mfma_f32_32x32x16_bf16 v[82:97], v[2:5], v[2:5], 0
	v_mfma_f32_32x32x16_bf16 v[98:113], v[2:5], v[2:5], 0
	v_mfma_f32_32x32x16_bf16 v[114:129], v[2:5], v[2:5], 0
	s_addc_u32 s42, s21, 0
	s_mov_b32 s43, -2
	.p2align 6

;     __device__ __forceinline__ const char* pa(const Unit& u) const { return (const char*)(A + (size_t)u.pm * a_tile_stride + (size_t)((u.pn >> a_group_shift) * a_group_cols)); }
;     __device__ __forceinline__ const char* pb(const Unit& u) const { return (const char*)(Bt + (size_t)u.pn * b_tile_stride); }
;     __device__ __forceinline__ const char* pa(const Unit& u) const { return (const char*)(A + (size_t)u.pm * a_tile_stride + (size_t)u.pn * 512); }
; template <class PT, class Epi>
; __device__ __forceinline__ void gemm_phase_once(LAS unsigned char* lds, const PT& S, const Epi& E, bool epi_on) {
;     ...
;         const bool has_next = S.next(ui + 1, nxt);
;         const char* nA = has_next ? S.pa(nxt) : cA; const char* nB = has_next ? S.pb(nxt) : cB;
;         for (int t = 0; t < nt; t += 2) {
;             const bool last = (t == nt - 2);
;             const char* a1 = cA + (size_t)(t + 1) * kstep;
;             const char* a2 = last ? nA : cA + (size_t)(t + 2) * kstep; const char* b2 = last ? nB : cB + (size_t)(t + 2) * kstep;
;             const char* a3 = a2 + kstep; const char* b3 = b2 + kstep;
;     ...
; #pragma unroll
;         for (int a = 0; a < 2; ++a)
; #pragma unroll
;             for (int b = 0; b < 2; ++b)
; #pragma unroll
;                 for (int m = 0; m < 4; ++m)
; #pragma unroll
;                     for (int n = 0; n < 2; ++n) acc[a][b][m][n] = (f32x4){0.f, 0.f, 0.f, 0.f};
.LBB0_779:
	s_ashr_i32 s13, s12, 31
	v_cmp_lt_i64_e64 s[24:25], s[14:15], 16
	s_lshl_b64 s[14:15], s[12:13], 20
	s_add_u32 s14, s81, s14
	s_addc_u32 s15, s96, s15
	s_and_b64 s[16:17], s[24:25], exec
	s_cselect_b32 s1, s15, s21
	s_cselect_b32 s13, s14, s20
	s_ashr_i32 s11, s10, 31
	s_lshl_b64 s[16:17], s[10:11], 20
	s_add_u32 s16, s82, s16
	s_addc_u32 s17, s83, s17
	s_and_b64 s[24:25], s[24:25], exec
	s_cselect_b32 s11, s17, s23
	s_cselect_b32 s19, s16, s22
	s_add_u32 s20, s20, 0x80080
	s_addc_u32 s21, s21, 0
	s_add_u32 s45, s22, 0x100
	v_mov_b32_e32 v2, 0
	v_mov_b32_e32 v3, 0
	v_mov_b32_e32 v4, 0
	v_mov_b32_e32 v5, 0
	s_nop 1
	v_mfma_f32_16x16x32_bf16 v[6:9], v[2:5], v[2:5], 0
	v_mfma_f32_16x16x32_bf16 v[10:13], v[2:5], v[2:5], 0
	v_mfma_f32_16x16x32_bf16 v[14:17], v[2:5], v[2:5], 0
	v_mfma_f32_32x32x16_bf16 v[18:33], v[2:5], v[2:5], 0
	v_mfma_f32_32x32x16_bf16 v[34:49], v[2:5], v[2:5], 0
	v_mfma_f32_32x32x16_bf16 v[50:65], v[2:5], v[2:5], 0
	v_mfma_f32_32x32x16_bf16 v[66:81], v[2:5], v[2:5], 0
	v_mfma_f32_32x32x16_bf16 v[82:97], v[2:5], v[2:5], 0
	v_mfma_f32_32x32x16_bf16 v[98:113], v[2:5], v[2:5], 0
	v_mfma_f32_32x32x16_bf16 v[114:129], v[2:5], v[2:5], 0
	s_addc_u32 s46, s23, 0
	s_mov_b32 s47, -2
	.p2align 6

;     __device__ __forceinline__ const char* pa(const Unit& u) const { return (const char*)(A + (size_t)u.pm * a_tile_stride + (size_t)((u.pn >> a_group_shift) * a_group_cols)); }
;     __device__ __forceinline__ const char* pb(const Unit& u) const { return (const char*)(Bt + (size_t)u.pn * b_tile_stride); }
;     __device__ __forceinline__ const char* pa(const Unit& u) const { return (const char*)(A + (size_t)u.pm * a_tile_stride + (size_t)u.pn * 512); }
; template <class PT, class Epi>
; __device__ __forceinline__ void gemm_phase_once(LAS unsigned char* lds, const PT& S, const Epi& E, bool epi_on) {
;     ...
;         const bool has_next = S.next(ui + 1, nxt);
;         const char* nA = has_next ? S.pa(nxt) : cA; const char* nB = has_next ? S.pb(nxt) : cB;
;         for (int t = 0; t < nt; t += 2) {
;             const bool last = (t == nt - 2);
;             const char* a1 = cA + (size_t)(t + 1) * kstep;
;             const char* a2 = last ? nA : cA + (size_t)(t + 2) * kstep; const char* b2 = last ? nB : cB + (size_t)(t + 2) * kstep;
;             const char* a3 = a2 + kstep; const char* b3 = b2 + kstep;
;     ...
; #pragma unroll
;         for (int a = 0; a < 2; ++a)
; #pragma unroll
;             for (int b = 0; b < 2; ++b)
; #pragma unroll
;                 for (int m = 0; m < 4; ++m)
; #pragma unroll
;                     for (int n = 0; n < 2; ++n) acc[a][b][m][n] = (f32x4){0.f, 0.f, 0.f, 0.f};
.LBB0_1125:
	s_ashr_i32 s13, s12, 31
	v_cmp_lt_i64_e32 vcc, s[14:15], v[144:145]
	s_lshl_b64 s[14:15], s[12:13], 18
	v_readlane_b32 s16, v254, 48
	v_readlane_b32 s17, v254, 49
	s_add_u32 s14, s16, s14
	s_addc_u32 s15, s17, s15
	s_and_b64 s[16:17], vcc, exec
	s_cselect_b32 s13, s15, s19
	s_cselect_b32 s39, s14, s18
	s_ashr_i32 s9, s8, 31
	s_lshl_b64 s[16:17], s[8:9], 18
	v_readlane_b32 s22, v254, 7
	v_readlane_b32 s23, v254, 8
	s_add_u32 s16, s22, s16
	s_addc_u32 s17, s23, s17
	s_and_b64 s[22:23], vcc, exec
	s_cselect_b32 s9, s17, s21
	s_cselect_b32 s40, s16, s20
	s_add_u32 s18, s18, 0x20080
	s_addc_u32 s19, s19, 0
	s_add_u32 s41, s20, 0x100
	v_mov_b32_e32 v4, 0
	v_mov_b32_e32 v5, 0
	v_mov_b32_e32 v6, 0
	v_mov_b32_e32 v7, 0
	s_nop 1
	v_mfma_f32_16x16x32_bf16 v[8:11], v[4:7], v[4:7], 0
	v_mfma_f32_16x16x32_bf16 v[12:15], v[4:7], v[4:7], 0
	v_mfma_f32_16x16x32_bf16 v[16:19], v[4:7], v[4:7], 0
	v_mfma_f32_32x32x16_bf16 v[20:35], v[4:7], v[4:7], 0
	v_mfma_f32_32x32x16_bf16 v[36:51], v[4:7], v[4:7], 0
	v_mfma_f32_32x32x16_bf16 v[52:67], v[4:7], v[4:7], 0
	v_mfma_f32_32x32x16_bf16 v[68:83], v[4:7], v[4:7], 0
	v_mfma_f32_32x32x16_bf16 v[84:99], v[4:7], v[4:7], 0
	v_mfma_f32_32x32x16_bf16 v[100:115], v[4:7], v[4:7], 0
	v_mfma_f32_32x32x16_bf16 v[116:131], v[4:7], v[4:7], 0
	s_addc_u32 s42, s21, 0
	s_mov_b32 s43, -2
	.p2align 6

;     __device__ __forceinline__ const char* pa(const Unit& u) const { return (const char*)(A + (size_t)u.pm * a_tile_stride + (size_t)((u.pn >> a_group_shift) * a_group_cols)); }
;     __device__ __forceinline__ const char* pb(const Unit& u) const { return (const char*)(Bt + (size_t)u.pn * b_tile_stride); }
;     __device__ __forceinline__ const char* pa(const Unit& u) const { return (const char*)(A + (size_t)u.pm * a_tile_stride + (size_t)u.pn * 512); }
; template <class PT, class Epi>
; __device__ __forceinline__ void gemm_phase_once(LAS unsigned char* lds, const PT& S, const Epi& E, bool epi_on) {
;     ...
;         const bool has_next = S.next(ui + 1, nxt);
;         const char* nA = has_next ? S.pa(nxt) : cA; const char* nB = has_next ? S.pb(nxt) : cB;
;         for (int t = 0; t < nt; t += 2) {
;             const bool last = (t == nt - 2);
;             const char* a1 = cA + (size_t)(t + 1) * kstep;
;             const char* a2 = last ? nA : cA + (size_t)(t + 2) * kstep; const char* b2 = last ? nB : cB + (size_t)(t + 2) * kstep;
;             const char* a3 = a2 + kstep; const char* b3 = b2 + kstep;
;     ...
; #pragma unroll
;         for (int a = 0; a < 2; ++a)
; #pragma unroll
;             for (int b = 0; b < 2; ++b)
; #pragma unroll
;                 for (int m = 0; m < 4; ++m)
; #pragma unroll
;                     for (int n = 0; n < 2; ++n) acc[a][b][m][n] = (f32x4){0.f, 0.f, 0.f, 0.f};
.LBB0_1252:
	s_ashr_i32 s23, s22, 31
	v_cmp_lt_i64_e32 vcc, s[24:25], v[154:155]
	s_lshl_b64 s[24:25], s[22:23], 20
	s_add_u32 s24, s72, s24
	s_addc_u32 s25, s73, s25
	s_and_b64 s[26:27], vcc, exec
	s_cselect_b32 s23, s25, s31
	s_cselect_b32 s29, s24, s30
	s_ashr_i32 s21, s20, 31
	s_lshl_b64 s[26:27], s[20:21], 20
	s_add_u32 s26, s76, s26
	s_addc_u32 s27, s77, s27
	s_and_b64 s[36:37], vcc, exec
	s_cselect_b32 s21, s27, s35
	s_cselect_b32 s58, s26, s34
	s_add_u32 s59, s34, 0x100
	v_mov_b32_e32 v4, 0
	v_mov_b32_e32 v5, 0
	v_mov_b32_e32 v6, 0
	v_mov_b32_e32 v7, 0
	s_nop 1
	v_mfma_f32_16x16x32_bf16 v[8:11], v[4:7], v[4:7], 0
	v_mfma_f32_16x16x32_bf16 v[12:15], v[4:7], v[4:7], 0
	v_mfma_f32_16x16x32_bf16 v[16:19], v[4:7], v[4:7], 0
	v_mfma_f32_32x32x16_bf16 v[20:35], v[4:7], v[4:7], 0
	v_mfma_f32_32x32x16_bf16 v[44:59], v[4:7], v[4:7], 0
	v_mfma_f32_32x32x16_bf16 v[60:75], v[4:7], v[4:7], 0
	v_mfma_f32_32x32x16_bf16 v[76:91], v[4:7], v[4:7], 0
	v_mfma_f32_32x32x16_bf16 v[92:107], v[4:7], v[4:7], 0
	v_mfma_f32_32x32x16_bf16 v[108:123], v[4:7], v[4:7], 0
	v_mfma_f32_32x32x16_bf16 v[124:139], v[4:7], v[4:7], 0
	s_addc_u32 s60, s35, 0
	s_mov_b32 s61, -2
	s_waitcnt lgkmcnt(0)
	s_waitcnt vmcnt(0)
	.p2align 6

;     __device__ __forceinline__ const char* pa(const Unit& u) const { return (const char*)(A + (size_t)u.pm * a_tile_stride + (size_t)((u.pn >> a_group_shift) * a_group_cols)); }
;     __device__ __forceinline__ const char* pb(const Unit& u) const { return (const char*)(Bt + (size_t)u.pn * b_tile_stride); }
;     __device__ __forceinline__ const char* pa(const Unit& u) const { return (const char*)(A + (size_t)u.pm * a_tile_stride + (size_t)u.pn * 512); }
; template <class PT, class Epi>
; __device__ __forceinline__ void gemm_phase_once(LAS unsigned char* lds, const PT& S, const Epi& E, bool epi_on) {
;     ...
;         const bool has_next = S.next(ui + 1, nxt);
;         const char* nA = has_next ? S.pa(nxt) : cA; const char* nB = has_next ? S.pb(nxt) : cB;
;         for (int t = 0; t < nt; t += 2) {
;             const bool last = (t == nt - 2);
;             const char* a1 = cA + (size_t)(t + 1) * kstep;
;             const char* a2 = last ? nA : cA + (size_t)(t + 2) * kstep; const char* b2 = last ? nB : cB + (size_t)(t + 2) * kstep;
;             const char* a3 = a2 + kstep; const char* b3 = b2 + kstep;
;     ...
; #pragma unroll
;         for (int a = 0; a < 2; ++a)
; #pragma unroll
;             for (int b = 0; b < 2; ++b)
; #pragma unroll
;                 for (int m = 0; m < 4; ++m)
; #pragma unroll
;                     for (int n = 0; n < 2; ++n) acc[a][b][m][n] = (f32x4){0.f, 0.f, 0.f, 0.f};
.LBB0_1411:
	s_add_u32 s12, s12, 0x160080
	s_addc_u32 s13, s13, 0
	s_add_u32 s37, s14, 0x100
	v_mov_b32_e32 v4, 0
	v_mov_b32_e32 v5, 0
	v_mov_b32_e32 v6, 0
	v_mov_b32_e32 v7, 0
	s_nop 1
	v_mfma_f32_16x16x32_bf16 v[8:11], v[4:7], v[4:7], 0
	v_mfma_f32_16x16x32_bf16 v[12:15], v[4:7], v[4:7], 0
	v_mfma_f32_16x16x32_bf16 v[16:19], v[4:7], v[4:7], 0
	v_mfma_f32_32x32x16_bf16 v[20:35], v[4:7], v[4:7], 0
	v_mfma_f32_32x32x16_bf16 v[36:51], v[4:7], v[4:7], 0
	v_mfma_f32_32x32x16_bf16 v[52:67], v[4:7], v[4:7], 0
	v_mfma_f32_32x32x16_bf16 v[68:83], v[4:7], v[4:7], 0
	v_mfma_f32_32x32x16_bf16 v[84:99], v[4:7], v[4:7], 0
	v_mfma_f32_32x32x16_bf16 v[100:115], v[4:7], v[4:7], 0
	v_mfma_f32_32x32x16_bf16 v[116:131], v[4:7], v[4:7], 0
	s_addc_u32 s38, s15, 0
	s_mov_b32 s39, -2
	s_waitcnt lgkmcnt(0)
	.p2align 6

;     __device__ __forceinline__ const char* pa(const Unit& u) const { return (const char*)(A + (size_t)u.pm * a_tile_stride + (size_t)((u.pn >> a_group_shift) * a_group_cols)); }
;     __device__ __forceinline__ const char* pb(const Unit& u) const { return (const char*)(Bt + (size_t)u.pn * b_tile_stride); }
;     __device__ __forceinline__ const char* pa(const Unit& u) const { return (const char*)(A + (size_t)u.pm * a_tile_stride + (size_t)u.pn * 512); }
; template <class PT, class Epi>
; __device__ __forceinline__ void gemm_phase_once(LAS unsigned char* lds, const PT& S, const Epi& E, bool epi_on) {
;     ...
;         const bool has_next = S.next(ui + 1, nxt);
;         const char* nA = has_next ? S.pa(nxt) : cA; const char* nB = has_next ? S.pb(nxt) : cB;
;         for (int t = 0; t < nt; t += 2) {
;             const bool last = (t == nt - 2);
;             const char* a1 = cA + (size_t)(t + 1) * kstep;
;             const char* a2 = last ? nA : cA + (size_t)(t + 2) * kstep; const char* b2 = last ? nB : cB + (size_t)(t + 2) * kstep;
;             const char* a3 = a2 + kstep; const char* b3 = b2 + kstep;
;     ...
; #pragma unroll
;         for (int a = 0; a < 2; ++a)
; #pragma unroll
;             for (int b = 0; b < 2; ++b)
; #pragma unroll
;                 for (int m = 0; m < 4; ++m)
; #pragma unroll
;                     for (int n = 0; n < 2; ++n) acc[a][b][m][n] = (f32x4){0.f, 0.f, 0.f, 0.f};
.LBB0_1734:
	s_ashr_i32 s15, s14, 31
	s_xor_b64 s[24:25], s[0:1], -1
	s_lshl_b64 s[22:23], s[14:15], 20
	s_add_u32 s22, s72, s22
	s_addc_u32 s23, s73, s23
	s_and_b64 s[26:27], s[0:1], exec
	s_cselect_b32 s3, s23, s31
	s_cselect_b32 s15, s22, s30
	s_ashr_i32 s21, s20, 31
	s_lshl_b64 s[26:27], s[20:21], 20
	v_readlane_b32 s34, v254, 5
	v_readlane_b32 s35, v254, 6
	s_add_u32 s26, s34, s26
	s_addc_u32 s27, s35, s27
	s_and_b64 s[0:1], s[0:1], exec
	s_cselect_b32 s21, s27, s29
	s_cselect_b32 s34, s26, s28
	s_add_u32 s0, s30, 0x80080
	s_addc_u32 s1, s31, 0
	s_add_u32 s35, s28, 0x100
	v_mov_b32_e32 v4, 0
	v_mov_b32_e32 v5, 0
	v_mov_b32_e32 v6, 0
	v_mov_b32_e32 v7, 0
	s_nop 1
	v_mfma_f32_16x16x32_bf16 v[8:11], v[4:7], v[4:7], 0
	v_mfma_f32_16x16x32_bf16 v[12:15], v[4:7], v[4:7], 0
	v_mfma_f32_16x16x32_bf16 v[16:19], v[4:7], v[4:7], 0
	v_mfma_f32_32x32x16_bf16 v[20:35], v[4:7], v[4:7], 0
	v_mfma_f32_32x32x16_bf16 v[36:51], v[4:7], v[4:7], 0
	v_mfma_f32_32x32x16_bf16 v[52:67], v[4:7], v[4:7], 0
	v_mfma_f32_32x32x16_bf16 v[68:83], v[4:7], v[4:7], 0
	v_mfma_f32_32x32x16_bf16 v[84:99], v[4:7], v[4:7], 0
	v_mfma_f32_32x32x16_bf16 v[100:115], v[4:7], v[4:7], 0
	v_mfma_f32_32x32x16_bf16 v[116:131], v[4:7], v[4:7], 0
	s_addc_u32 s53, s29, 0
	s_mov_b32 s56, -2
	s_waitcnt lgkmcnt(0)
	s_waitcnt vmcnt(0)
	.p2align 6

;     __device__ __forceinline__ const char* pa(const Unit& u) const { return (const char*)(A + (size_t)u.pm * a_tile_stride + (size_t)((u.pn >> a_group_shift) * a_group_cols)); }
;     __device__ __forceinline__ const char* pb(const Unit& u) const { return (const char*)(Bt + (size_t)u.pn * b_tile_stride); }
;     __device__ __forceinline__ const char* pa(const Unit& u) const { return (const char*)(A + (size_t)u.pm * a_tile_stride + (size_t)u.pn * 512); }
; template <class PT, class Epi>
; __device__ __forceinline__ void gemm_phase_once(LAS unsigned char* lds, const PT& S, const Epi& E, bool epi_on) {
;     ...
;         const bool has_next = S.next(ui + 1, nxt);
;         const char* nA = has_next ? S.pa(nxt) : cA; const char* nB = has_next ? S.pb(nxt) : cB;
;         for (int t = 0; t < nt; t += 2) {
;             const bool last = (t == nt - 2);
;             const char* a1 = cA + (size_t)(t + 1) * kstep;
;             const char* a2 = last ? nA : cA + (size_t)(t + 2) * kstep; const char* b2 = last ? nB : cB + (size_t)(t + 2) * kstep;
;             const char* a3 = a2 + kstep; const char* b3 = b2 + kstep;
.LBB0_1956:
	s_ashr_i32 s46, s22, 4
	s_ashr_i32 s47, s46, 31
	s_lshl_b64 s[46:47], s[46:47], 21
	v_readlane_b32 s48, v254, 52
	v_readlane_b32 s49, v254, 53
	s_add_u32 s21, s48, s46
	s_addc_u32 s23, s49, s47
	s_add_u32 s24, s21, s24
	s_addc_u32 s25, s23, s25
	s_and_b64 s[6:7], s[6:7], exec
	s_cselect_b32 s21, s25, s27
	s_cselect_b32 s23, s24, s26
	s_add_u32 s6, s28, 0x80080
	s_addc_u32 s7, s29, 0
	s_add_u32 s45, s26, 0x100
	v_mov_b32_e32 v4, 0
	v_mov_b32_e32 v5, 0
	v_mov_b32_e32 v6, 0
	v_mov_b32_e32 v7, 0
	s_nop 1
	v_mfma_f32_16x16x32_bf16 v[8:11], v[4:7], v[4:7], 0
	v_mfma_f32_16x16x32_bf16 v[12:15], v[4:7], v[4:7], 0
	v_mfma_f32_16x16x32_bf16 v[16:19], v[4:7], v[4:7], 0
	v_mfma_f32_32x32x16_bf16 v[20:35], v[4:7], v[4:7], 0
	v_mfma_f32_32x32x16_bf16 v[36:51], v[4:7], v[4:7], 0
	v_mfma_f32_32x32x16_bf16 v[52:67], v[4:7], v[4:7], 0
	v_mfma_f32_32x32x16_bf16 v[68:83], v[4:7], v[4:7], 0
	v_mfma_f32_32x32x16_bf16 v[84:99], v[4:7], v[4:7], 0
	v_mfma_f32_32x32x16_bf16 v[100:115], v[4:7], v[4:7], 0
	v_mfma_f32_32x32x16_bf16 v[116:131], v[4:7], v[4:7], 0
	s_addc_u32 s46, s27, 0
	s_mov_b32 s47, -2
	s_waitcnt lgkmcnt(0)
	.p2align 6

;     __device__ __forceinline__ const char* pa(const Unit& u) const { return (const char*)(A + (size_t)u.pm * a_tile_stride + (size_t)((u.pn >> a_group_shift) * a_group_cols)); }
;     __device__ __forceinline__ const char* pb(const Unit& u) const { return (const char*)(Bt + (size_t)u.pn * b_tile_stride); }
;     __device__ __forceinline__ const char* pa(const Unit& u) const { return (const char*)(A + (size_t)u.pm * a_tile_stride + (size_t)u.pn * 512); }
; template <class PT, class Epi>
; __device__ __forceinline__ void gemm_phase_once(LAS unsigned char* lds, const PT& S, const Epi& E, bool epi_on) {
;     ...
;         const bool has_next = S.next(ui + 1, nxt);
;         const char* nA = has_next ? S.pa(nxt) : cA; const char* nB = has_next ? S.pb(nxt) : cB;
;         for (int t = 0; t < nt; t += 2) {
;             const bool last = (t == nt - 2);
;             const char* a1 = cA + (size_t)(t + 1) * kstep;
;             const char* a2 = last ? nA : cA + (size_t)(t + 2) * kstep; const char* b2 = last ? nB : cB + (size_t)(t + 2) * kstep;
;             const char* a3 = a2 + kstep; const char* b3 = b2 + kstep;
;     ...
; #pragma unroll
;         for (int a = 0; a < 2; ++a)
; #pragma unroll
;             for (int b = 0; b < 2; ++b)
; #pragma unroll
;                 for (int m = 0; m < 4; ++m)
; #pragma unroll
;                     for (int n = 0; n < 2; ++n) acc[a][b][m][n] = (f32x4){0.f, 0.f, 0.f, 0.f};
.LBB0_2421:
	s_ashr_i32 s15, s14, 31
	v_cmp_lt_i64_e32 vcc, s[16:17], v[144:145]
	s_lshl_b64 s[16:17], s[14:15], 20
	s_add_u32 s16, s78, s16
	s_addc_u32 s17, s79, s17
	s_and_b64 s[18:19], vcc, exec
	s_cselect_b32 s15, s17, s21
	s_cselect_b32 s41, s16, s20
	s_ashr_i32 s11, s10, 31
	s_lshl_b64 s[18:19], s[10:11], 20
	s_add_u32 s18, s92, s18
	s_addc_u32 s19, s93, s19
	s_and_b64 s[24:25], vcc, exec
	s_cselect_b32 s11, s19, s23
	s_cselect_b32 s42, s18, s22
	s_add_u32 s20, s20, 0x80080
	s_addc_u32 s21, s21, 0
	s_add_u32 s43, s22, 0x100
	v_mov_b32_e32 v4, 0
	v_mov_b32_e32 v5, 0
	v_mov_b32_e32 v6, 0
	v_mov_b32_e32 v7, 0
	s_nop 1
	v_mfma_f32_16x16x32_bf16 v[8:11], v[4:7], v[4:7], 0
	v_mfma_f32_16x16x32_bf16 v[12:15], v[4:7], v[4:7], 0
	v_mfma_f32_16x16x32_bf16 v[16:19], v[4:7], v[4:7], 0
	v_mfma_f32_32x32x16_bf16 v[20:35], v[4:7], v[4:7], 0
	v_mfma_f32_32x32x16_bf16 v[36:51], v[4:7], v[4:7], 0
	v_mfma_f32_32x32x16_bf16 v[52:67], v[4:7], v[4:7], 0
	v_mfma_f32_32x32x16_bf16 v[68:83], v[4:7], v[4:7], 0
	v_mfma_f32_32x32x16_bf16 v[84:99], v[4:7], v[4:7], 0
	v_mfma_f32_32x32x16_bf16 v[100:115], v[4:7], v[4:7], 0
	v_mfma_f32_32x32x16_bf16 v[116:131], v[4:7], v[4:7], 0
	s_addc_u32 s44, s23, 0
	s_mov_b32 s45, -2
	s_waitcnt lgkmcnt(0)
	.p2align 6

;     __device__ __forceinline__ const char* pa(const Unit& u) const { return (const char*)(A + (size_t)u.pm * a_tile_stride + (size_t)((u.pn >> a_group_shift) * a_group_cols)); }
;     __device__ __forceinline__ const char* pb(const Unit& u) const { return (const char*)(Bt + (size_t)u.pn * b_tile_stride); }
;     __device__ __forceinline__ const char* pa(const Unit& u) const { return (const char*)(A + (size_t)u.pm * a_tile_stride + (size_t)u.pn * 512); }
; template <class PT, class Epi>
; __device__ __forceinline__ void gemm_phase_once(LAS unsigned char* lds, const PT& S, const Epi& E, bool epi_on) {
;     ...
;         const bool has_next = S.next(ui + 1, nxt);
;         const char* nA = has_next ? S.pa(nxt) : cA; const char* nB = has_next ? S.pb(nxt) : cB;
;         for (int t = 0; t < nt; t += 2) {
;             const bool last = (t == nt - 2);
;             const char* a1 = cA + (size_t)(t + 1) * kstep;
;             const char* a2 = last ? nA : cA + (size_t)(t + 2) * kstep; const char* b2 = last ? nB : cB + (size_t)(t + 2) * kstep;
;             const char* a3 = a2 + kstep; const char* b3 = b2 + kstep;
;     ...
; #pragma unroll
;         for (int a = 0; a < 2; ++a)
; #pragma unroll
;             for (int b = 0; b < 2; ++b)
; #pragma unroll
;                 for (int m = 0; m < 4; ++m)
; #pragma unroll
;                     for (int n = 0; n < 2; ++n) acc[a][b][m][n] = (f32x4){0.f, 0.f, 0.f, 0.f};
.LBB0_2555:
	s_ashr_i32 s13, s12, 31
	v_cmp_lt_i64_e32 vcc, s[14:15], v[144:145]
	s_lshl_b64 s[14:15], s[12:13], 20
	s_add_u32 s14, s72, s14
	s_addc_u32 s15, s73, s15
	s_and_b64 s[16:17], vcc, exec
	s_cselect_b32 s13, s15, s21
	s_cselect_b32 s41, s14, s20
	s_ashr_i32 s11, s10, 31
	s_lshl_b64 s[16:17], s[10:11], 20
	s_add_u32 s16, s84, s16
	s_addc_u32 s17, s85, s17
	s_and_b64 s[24:25], vcc, exec
	s_cselect_b32 s11, s17, s23
	s_cselect_b32 s42, s16, s22
	s_add_u32 s20, s20, 0x80080
	s_addc_u32 s21, s21, 0
	s_add_u32 s43, s22, 0x100
	v_mov_b32_e32 v4, 0
	v_mov_b32_e32 v5, 0
	v_mov_b32_e32 v6, 0
	v_mov_b32_e32 v7, 0
	s_nop 1
	v_mfma_f32_16x16x32_bf16 v[8:11], v[4:7], v[4:7], 0
	v_mfma_f32_16x16x32_bf16 v[12:15], v[4:7], v[4:7], 0
	v_mfma_f32_16x16x32_bf16 v[16:19], v[4:7], v[4:7], 0
	v_mfma_f32_32x32x16_bf16 v[20:35], v[4:7], v[4:7], 0
	v_mfma_f32_32x32x16_bf16 v[36:51], v[4:7], v[4:7], 0
	v_mfma_f32_32x32x16_bf16 v[52:67], v[4:7], v[4:7], 0
	v_mfma_f32_32x32x16_bf16 v[68:83], v[4:7], v[4:7], 0
	v_mfma_f32_32x32x16_bf16 v[84:99], v[4:7], v[4:7], 0
	v_mfma_f32_32x32x16_bf16 v[100:115], v[4:7], v[4:7], 0
	v_mfma_f32_32x32x16_bf16 v[116:131], v[4:7], v[4:7], 0
	s_addc_u32 s44, s23, 0
	s_mov_b32 s45, -2
	s_waitcnt lgkmcnt(0)
	s_waitcnt vmcnt(0)
	.p2align 6

;     __device__ __forceinline__ const char* pa(const Unit& u) const { return (const char*)(A + (size_t)u.pm * a_tile_stride + (size_t)((u.pn >> a_group_shift) * a_group_cols)); }
;     __device__ __forceinline__ const char* pb(const Unit& u) const { return (const char*)(Bt + (size_t)u.pn * b_tile_stride); }
;     __device__ __forceinline__ const char* pa(const Unit& u) const { return (const char*)(A + (size_t)u.pm * a_tile_stride + (size_t)u.pn * 512); }
; template <class PT, class Epi>
; __device__ __forceinline__ void gemm_phase_once(LAS unsigned char* lds, const PT& S, const Epi& E, bool epi_on) {
;     ...
;         const bool has_next = S.next(ui + 1, nxt);
;         const char* nA = has_next ? S.pa(nxt) : cA; const char* nB = has_next ? S.pb(nxt) : cB;
;         for (int t = 0; t < nt; t += 2) {
;             const bool last = (t == nt - 2);
;             const char* a1 = cA + (size_t)(t + 1) * kstep;
;             const char* a2 = last ? nA : cA + (size_t)(t + 2) * kstep; const char* b2 = last ? nB : cB + (size_t)(t + 2) * kstep;
;             const char* a3 = a2 + kstep; const char* b3 = b2 + kstep;
;     ...
; #pragma unroll
;         for (int a = 0; a < 2; ++a)
; #pragma unroll
;             for (int b = 0; b < 2; ++b)
; #pragma unroll
;                 for (int m = 0; m < 4; ++m)
; #pragma unroll
;                     for (int n = 0; n < 2; ++n) acc[a][b][m][n] = (f32x4){0.f, 0.f, 0.f, 0.f};
.LBB0_2578:
	s_ashr_i32 s15, s14, 31
	v_cmp_lt_i64_e64 s[26:27], s[16:17], 16
	s_lshl_b64 s[16:17], s[14:15], 20
	s_add_u32 s16, s81, s16
	s_addc_u32 s17, s96, s17
	s_and_b64 s[18:19], s[26:27], exec
	s_cselect_b32 s1, s17, s23
	s_cselect_b32 s15, s16, s22
	s_ashr_i32 s13, s12, 31
	s_lshl_b64 s[18:19], s[12:13], 20
	s_add_u32 s18, s82, s18
	s_addc_u32 s19, s83, s19
	s_and_b64 s[26:27], s[26:27], exec
	s_cselect_b32 s13, s19, s25
	s_cselect_b32 s21, s18, s24
	s_add_u32 s22, s22, 0x80080
	s_addc_u32 s23, s23, 0
	s_add_u32 s47, s24, 0x100
	v_mov_b32_e32 v4, 0
	v_mov_b32_e32 v5, 0
	v_mov_b32_e32 v6, 0
	v_mov_b32_e32 v7, 0
	s_nop 1
	v_mfma_f32_16x16x32_bf16 v[8:11], v[4:7], v[4:7], 0
	v_mfma_f32_16x16x32_bf16 v[12:15], v[4:7], v[4:7], 0
	v_mfma_f32_16x16x32_bf16 v[16:19], v[4:7], v[4:7], 0
	v_mfma_f32_32x32x16_bf16 v[20:35], v[4:7], v[4:7], 0
	v_mfma_f32_32x32x16_bf16 v[36:51], v[4:7], v[4:7], 0
	v_mfma_f32_32x32x16_bf16 v[52:67], v[4:7], v[4:7], 0
	v_mfma_f32_32x32x16_bf16 v[68:83], v[4:7], v[4:7], 0
	v_mfma_f32_32x32x16_bf16 v[84:99], v[4:7], v[4:7], 0
	v_mfma_f32_32x32x16_bf16 v[100:115], v[4:7], v[4:7], 0
	v_mfma_f32_32x32x16_bf16 v[116:131], v[4:7], v[4:7], 0
	s_addc_u32 s48, s25, 0
	s_mov_b32 s49, -2
	s_waitcnt lgkmcnt(0)
	.p2align 6

;     __device__ __forceinline__ const char* pa(const Unit& u) const { return (const char*)(A + (size_t)u.pm * a_tile_stride + (size_t)((u.pn >> a_group_shift) * a_group_cols)); }
;     __device__ __forceinline__ const char* pb(const Unit& u) const { return (const char*)(Bt + (size_t)u.pn * b_tile_stride); }
;     __device__ __forceinline__ const char* pa(const Unit& u) const { return (const char*)(A + (size_t)u.pm * a_tile_stride + (size_t)u.pn * 512); }
; template <class PT, class Epi>
; __device__ __forceinline__ void gemm_phase_once(LAS unsigned char* lds, const PT& S, const Epi& E, bool epi_on) {
;     ...
;         const bool has_next = S.next(ui + 1, nxt);
;         const char* nA = has_next ? S.pa(nxt) : cA; const char* nB = has_next ? S.pb(nxt) : cB;
;         for (int t = 0; t < nt; t += 2) {
;             const bool last = (t == nt - 2);
;             const char* a1 = cA + (size_t)(t + 1) * kstep;
;             const char* a2 = last ? nA : cA + (size_t)(t + 2) * kstep; const char* b2 = last ? nB : cB + (size_t)(t + 2) * kstep;
;             const char* a3 = a2 + kstep; const char* b3 = b2 + kstep;
;     ...
; #pragma unroll
;         for (int a = 0; a < 2; ++a)
; #pragma unroll
;             for (int b = 0; b < 2; ++b)
; #pragma unroll
;                 for (int m = 0; m < 4; ++m)
; #pragma unroll
;                     for (int n = 0; n < 2; ++n) acc[a][b][m][n] = (f32x4){0.f, 0.f, 0.f, 0.f};
.LBB0_2855:
	s_ashr_i32 s15, s14, 31
	v_cmp_lt_i64_e32 vcc, s[16:17], v[144:145]
	s_lshl_b64 s[16:17], s[14:15], 18
	v_readlane_b32 s18, v254, 48
	v_readlane_b32 s19, v254, 49
	s_add_u32 s16, s18, s16
	s_addc_u32 s17, s19, s17
	s_and_b64 s[18:19], vcc, exec
	s_cselect_b32 s15, s17, s21
	s_cselect_b32 s41, s16, s20
	s_ashr_i32 s11, s10, 31
	s_lshl_b64 s[18:19], s[10:11], 18
	v_readlane_b32 s24, v254, 7
	v_readlane_b32 s25, v254, 8
	s_add_u32 s18, s24, s18
	s_addc_u32 s19, s25, s19
	s_and_b64 s[24:25], vcc, exec
	s_cselect_b32 s11, s19, s23
	s_cselect_b32 s42, s18, s22
	s_add_u32 s20, s20, 0x20080
	s_addc_u32 s21, s21, 0
	s_add_u32 s43, s22, 0x100
	v_mov_b32_e32 v4, 0
	v_mov_b32_e32 v5, 0
	v_mov_b32_e32 v6, 0
	v_mov_b32_e32 v7, 0
	s_nop 1
	v_mfma_f32_16x16x32_bf16 v[8:11], v[4:7], v[4:7], 0
	v_mfma_f32_16x16x32_bf16 v[12:15], v[4:7], v[4:7], 0
	v_mfma_f32_16x16x32_bf16 v[16:19], v[4:7], v[4:7], 0
	v_mfma_f32_32x32x16_bf16 v[20:35], v[4:7], v[4:7], 0
	v_mfma_f32_32x32x16_bf16 v[36:51], v[4:7], v[4:7], 0
	v_mfma_f32_32x32x16_bf16 v[52:67], v[4:7], v[4:7], 0
	v_mfma_f32_32x32x16_bf16 v[68:83], v[4:7], v[4:7], 0
	v_mfma_f32_32x32x16_bf16 v[84:99], v[4:7], v[4:7], 0
	v_mfma_f32_32x32x16_bf16 v[100:115], v[4:7], v[4:7], 0
	v_mfma_f32_32x32x16_bf16 v[116:131], v[4:7], v[4:7], 0
	s_addc_u32 s44, s23, 0
	s_mov_b32 s45, -2
	s_waitcnt lgkmcnt(0)
	.p2align 6

;     __device__ __forceinline__ const char* pa(const Unit& u) const { return (const char*)(A + (size_t)u.pm * a_tile_stride + (size_t)((u.pn >> a_group_shift) * a_group_cols)); }
;     __device__ __forceinline__ const char* pb(const Unit& u) const { return (const char*)(Bt + (size_t)u.pn * b_tile_stride); }
;     __device__ __forceinline__ const char* pa(const Unit& u) const { return (const char*)(A + (size_t)u.pm * a_tile_stride + (size_t)u.pn * 512); }
; template <class PT, class Epi>
; __device__ __forceinline__ void gemm_phase_once(LAS unsigned char* lds, const PT& S, const Epi& E, bool epi_on) {
;     ...
;         const bool has_next = S.next(ui + 1, nxt);
;         const char* nA = has_next ? S.pa(nxt) : cA; const char* nB = has_next ? S.pb(nxt) : cB;
;         for (int t = 0; t < nt; t += 2) {
;             const bool last = (t == nt - 2);
;             const char* a1 = cA + (size_t)(t + 1) * kstep;
;             const char* a2 = last ? nA : cA + (size_t)(t + 2) * kstep; const char* b2 = last ? nB : cB + (size_t)(t + 2) * kstep;
;             const char* a3 = a2 + kstep; const char* b3 = b2 + kstep;
;     ...
; #pragma unroll
;         for (int a = 0; a < 2; ++a)
; #pragma unroll
;             for (int b = 0; b < 2; ++b)
; #pragma unroll
;                 for (int m = 0; m < 4; ++m)
; #pragma unroll
;                     for (int n = 0; n < 2; ++n) acc[a][b][m][n] = (f32x4){0.f, 0.f, 0.f, 0.f};
.LBB0_2982:
	s_ashr_i32 s29, s28, 31
	v_cmp_lt_i64_e32 vcc, s[30:31], v[154:155]
	s_lshl_b64 s[30:31], s[28:29], 20
	s_add_u32 s30, s72, s30
	s_addc_u32 s31, s73, s31
	s_and_b64 s[34:35], vcc, exec
	s_cselect_b32 s29, s31, s39
	s_cselect_b32 s37, s30, s38
	s_ashr_i32 s27, s26, 31
	s_lshl_b64 s[34:35], s[26:27], 20
	s_add_u32 s34, s76, s34
	s_addc_u32 s35, s77, s35
	s_and_b64 s[42:43], vcc, exec
	s_cselect_b32 s27, s35, s41
	s_cselect_b32 s64, s34, s40
	s_add_u32 s65, s40, 0x100
	v_mov_b32_e32 v4, 0
	v_mov_b32_e32 v5, 0
	v_mov_b32_e32 v6, 0
	v_mov_b32_e32 v7, 0
	s_nop 1
	v_mfma_f32_16x16x32_bf16 v[8:11], v[4:7], v[4:7], 0
	v_mfma_f32_16x16x32_bf16 v[12:15], v[4:7], v[4:7], 0
	v_mfma_f32_16x16x32_bf16 v[16:19], v[4:7], v[4:7], 0
	v_mfma_f32_32x32x16_bf16 v[20:35], v[4:7], v[4:7], 0
	v_mfma_f32_32x32x16_bf16 v[44:59], v[4:7], v[4:7], 0
	v_mfma_f32_32x32x16_bf16 v[60:75], v[4:7], v[4:7], 0
	v_mfma_f32_32x32x16_bf16 v[76:91], v[4:7], v[4:7], 0
	v_mfma_f32_32x32x16_bf16 v[92:107], v[4:7], v[4:7], 0
	v_mfma_f32_32x32x16_bf16 v[108:123], v[4:7], v[4:7], 0
	v_mfma_f32_32x32x16_bf16 v[124:139], v[4:7], v[4:7], 0
	s_addc_u32 s66, s41, 0
	s_mov_b32 s67, -2
	s_waitcnt lgkmcnt(0)
	s_waitcnt vmcnt(0)
	.p2align 6

;     __device__ __forceinline__ const char* pa(const Unit& u) const { return (const char*)(A + (size_t)u.pm * a_tile_stride + (size_t)((u.pn >> a_group_shift) * a_group_cols)); }
;     __device__ __forceinline__ const char* pb(const Unit& u) const { return (const char*)(Bt + (size_t)u.pn * b_tile_stride); }
;     __device__ __forceinline__ const char* pa(const Unit& u) const { return (const char*)(A + (size_t)u.pm * a_tile_stride + (size_t)u.pn * 512); }
; template <class PT, class Epi>
; __device__ __forceinline__ void gemm_phase_once(LAS unsigned char* lds, const PT& S, const Epi& E, bool epi_on) {
;     ...
;         const bool has_next = S.next(ui + 1, nxt);
;         const char* nA = has_next ? S.pa(nxt) : cA; const char* nB = has_next ? S.pb(nxt) : cB;
;         for (int t = 0; t < nt; t += 2) {
;             const bool last = (t == nt - 2);
;             const char* a1 = cA + (size_t)(t + 1) * kstep;
;             const char* a2 = last ? nA : cA + (size_t)(t + 2) * kstep; const char* b2 = last ? nB : cB + (size_t)(t + 2) * kstep;
;             const char* a3 = a2 + kstep; const char* b3 = b2 + kstep;
;     ...
; #pragma unroll
;         for (int a = 0; a < 2; ++a)
; #pragma unroll
;             for (int b = 0; b < 2; ++b)
; #pragma unroll
;                 for (int m = 0; m < 4; ++m)
; #pragma unroll
;                     for (int n = 0; n < 2; ++n) acc[a][b][m][n] = (f32x4){0.f, 0.f, 0.f, 0.f};
.LBB0_3141:
	s_add_u32 s14, s14, 0x160080
	s_addc_u32 s15, s15, 0
	s_add_u32 s39, s16, 0x100
	v_mov_b32_e32 v4, 0
	v_mov_b32_e32 v5, 0
	v_mov_b32_e32 v6, 0
	v_mov_b32_e32 v7, 0
	s_nop 1
	v_mfma_f32_16x16x32_bf16 v[8:11], v[4:7], v[4:7], 0
	v_mfma_f32_16x16x32_bf16 v[12:15], v[4:7], v[4:7], 0
	v_mfma_f32_16x16x32_bf16 v[16:19], v[4:7], v[4:7], 0
	v_mfma_f32_32x32x16_bf16 v[20:35], v[4:7], v[4:7], 0
	v_mfma_f32_32x32x16_bf16 v[36:51], v[4:7], v[4:7], 0
	v_mfma_f32_32x32x16_bf16 v[52:67], v[4:7], v[4:7], 0
	v_mfma_f32_32x32x16_bf16 v[68:83], v[4:7], v[4:7], 0
	v_mfma_f32_32x32x16_bf16 v[84:99], v[4:7], v[4:7], 0
	v_mfma_f32_32x32x16_bf16 v[100:115], v[4:7], v[4:7], 0
	v_mfma_f32_32x32x16_bf16 v[116:131], v[4:7], v[4:7], 0
	s_addc_u32 s40, s17, 0
	s_mov_b32 s41, -2
	s_waitcnt lgkmcnt(0)
	.p2align 6

;     __device__ __forceinline__ const char* pa(const Unit& u) const { return (const char*)(A + (size_t)u.pm * a_tile_stride + (size_t)((u.pn >> a_group_shift) * a_group_cols)); }
;     __device__ __forceinline__ const char* pb(const Unit& u) const { return (const char*)(Bt + (size_t)u.pn * b_tile_stride); }
;     __device__ __forceinline__ const char* pa(const Unit& u) const { return (const char*)(A + (size_t)u.pm * a_tile_stride + (size_t)u.pn * 512); }
; template <class PT, class Epi>
; __device__ __forceinline__ void gemm_phase_once(LAS unsigned char* lds, const PT& S, const Epi& E, bool epi_on) {
;     ...
;         const bool has_next = S.next(ui + 1, nxt);
;         const char* nA = has_next ? S.pa(nxt) : cA; const char* nB = has_next ? S.pb(nxt) : cB;
;         for (int t = 0; t < nt; t += 2) {
;             const bool last = (t == nt - 2);
;             const char* a1 = cA + (size_t)(t + 1) * kstep;
;             const char* a2 = last ? nA : cA + (size_t)(t + 2) * kstep; const char* b2 = last ? nB : cB + (size_t)(t + 2) * kstep;
;             const char* a3 = a2 + kstep; const char* b3 = b2 + kstep;
;     ...
; #pragma unroll
;         for (int a = 0; a < 2; ++a)
; #pragma unroll
;             for (int b = 0; b < 2; ++b)
; #pragma unroll
;                 for (int m = 0; m < 4; ++m)
; #pragma unroll
;                     for (int n = 0; n < 2; ++n) acc[a][b][m][n] = (f32x4){0.f, 0.f, 0.f, 0.f};
.LBB0_3457:
	s_ashr_i32 s9, s8, 31
	s_xor_b64 s[14:15], s[24:25], -1
	s_lshl_b64 s[12:13], s[8:9], 20
	s_add_u32 s12, s72, s12
	s_addc_u32 s13, s73, s13
	s_and_b64 s[16:17], s[24:25], exec
	s_cselect_b32 s9, s13, s21
	s_cselect_b32 s41, s12, s20
	s_ashr_i32 s11, s10, 31
	s_lshl_b64 s[16:17], s[10:11], 20
	v_readlane_b32 s42, v254, 5
	v_readlane_b32 s43, v254, 6
	s_add_u32 s16, s42, s16
	s_addc_u32 s17, s43, s17
	s_and_b64 s[24:25], s[24:25], exec
	s_cselect_b32 s11, s17, s23
	s_cselect_b32 s42, s16, s22
	s_add_u32 s20, s20, 0x80080
	s_addc_u32 s21, s21, 0
	s_add_u32 s43, s22, 0x100
	v_mov_b32_e32 v4, 0
	v_mov_b32_e32 v5, 0
	v_mov_b32_e32 v6, 0
	v_mov_b32_e32 v7, 0
	s_nop 1
	v_mfma_f32_16x16x32_bf16 v[8:11], v[4:7], v[4:7], 0
	v_mfma_f32_16x16x32_bf16 v[12:15], v[4:7], v[4:7], 0
	v_mfma_f32_16x16x32_bf16 v[16:19], v[4:7], v[4:7], 0
	v_mfma_f32_32x32x16_bf16 v[20:35], v[4:7], v[4:7], 0
	v_mfma_f32_32x32x16_bf16 v[36:51], v[4:7], v[4:7], 0
	v_mfma_f32_32x32x16_bf16 v[52:67], v[4:7], v[4:7], 0
	v_mfma_f32_32x32x16_bf16 v[68:83], v[4:7], v[4:7], 0
	v_mfma_f32_32x32x16_bf16 v[84:99], v[4:7], v[4:7], 0
	v_mfma_f32_32x32x16_bf16 v[100:115], v[4:7], v[4:7], 0
	v_mfma_f32_32x32x16_bf16 v[116:131], v[4:7], v[4:7], 0
	s_addc_u32 s44, s23, 0
	s_mov_b32 s45, -2
	s_waitcnt lgkmcnt(0)
	s_waitcnt vmcnt(0)
	.p2align 6

;     __device__ __forceinline__ const char* pa(const Unit& u) const { return (const char*)(A + (size_t)u.pm * a_tile_stride + (size_t)((u.pn >> a_group_shift) * a_group_cols)); }
;     __device__ __forceinline__ const char* pb(const Unit& u) const { return (const char*)(Bt + (size_t)u.pn * b_tile_stride); }
;     __device__ __forceinline__ const char* pa(const Unit& u) const { return (const char*)(A + (size_t)u.pm * a_tile_stride + (size_t)u.pn * 512); }
; template <class PT, class Epi>
; __device__ __forceinline__ void gemm_phase_once(LAS unsigned char* lds, const PT& S, const Epi& E, bool epi_on) {
;     ...
;         const bool has_next = S.next(ui + 1, nxt);
;         const char* nA = has_next ? S.pa(nxt) : cA; const char* nB = has_next ? S.pb(nxt) : cB;
;         for (int t = 0; t < nt; t += 2) {
;             const bool last = (t == nt - 2);
;             const char* a1 = cA + (size_t)(t + 1) * kstep;
;             const char* a2 = last ? nA : cA + (size_t)(t + 2) * kstep; const char* b2 = last ? nB : cB + (size_t)(t + 2) * kstep;
;             const char* a3 = a2 + kstep; const char* b3 = b2 + kstep;
;     ...
; #pragma unroll
;         for (int a = 0; a < 2; ++a)
; #pragma unroll
;             for (int b = 0; b < 2; ++b)
; #pragma unroll
;                 for (int m = 0; m < 4; ++m)
; #pragma unroll
;                     for (int n = 0; n < 2; ++n) acc[a][b][m][n] = (f32x4){0.f, 0.f, 0.f, 0.f};
.LBB0_3749:
	s_ashr_i32 s13, s12, 31
	v_cmp_lt_i64_e32 vcc, s[14:15], v[144:145]
	s_lshl_b64 s[14:15], s[12:13], 21
	s_add_u32 s14, s78, s14
	s_addc_u32 s15, s79, s15
	s_and_b64 s[16:17], vcc, exec
	s_cselect_b32 s13, s15, s19
	s_cselect_b32 s39, s14, s18
	s_ashr_i32 s9, s8, 31
	s_lshl_b64 s[16:17], s[8:9], 21
	s_add_u32 s16, s92, s16
	s_addc_u32 s17, s93, s17
	s_and_b64 s[22:23], vcc, exec
	s_cselect_b32 s9, s17, s21
	s_cselect_b32 s40, s16, s20
	s_add_u32 s18, s18, 0x100080
	s_addc_u32 s19, s19, 0
	s_add_u32 s41, s20, 0x100
	v_mov_b32_e32 v4, 0
	v_mov_b32_e32 v5, 0
	v_mov_b32_e32 v6, 0
	v_mov_b32_e32 v7, 0
	s_nop 1
	v_mfma_f32_16x16x32_bf16 v[8:11], v[4:7], v[4:7], 0
	v_mfma_f32_16x16x32_bf16 v[12:15], v[4:7], v[4:7], 0
	v_mfma_f32_16x16x32_bf16 v[16:19], v[4:7], v[4:7], 0
	v_mfma_f32_32x32x16_bf16 v[20:35], v[4:7], v[4:7], 0
	v_mfma_f32_32x32x16_bf16 v[36:51], v[4:7], v[4:7], 0
	v_mfma_f32_32x32x16_bf16 v[52:67], v[4:7], v[4:7], 0
	v_mfma_f32_32x32x16_bf16 v[68:83], v[4:7], v[4:7], 0
	v_mfma_f32_32x32x16_bf16 v[84:99], v[4:7], v[4:7], 0
	v_mfma_f32_32x32x16_bf16 v[100:115], v[4:7], v[4:7], 0
	v_mfma_f32_32x32x16_bf16 v[116:131], v[4:7], v[4:7], 0
	s_addc_u32 s42, s21, 0
	s_mov_b32 s43, -2
	s_waitcnt lgkmcnt(0)
	.p2align 6

;     __device__ __forceinline__ const char* pa(const Unit& u) const { return (const char*)(A + (size_t)u.pm * a_tile_stride + (size_t)((u.pn >> a_group_shift) * a_group_cols)); }
;     __device__ __forceinline__ const char* pb(const Unit& u) const { return (const char*)(Bt + (size_t)u.pn * b_tile_stride); }
;     __device__ __forceinline__ const char* pa(const Unit& u) const { return (const char*)(A + (size_t)u.pm * a_tile_stride + (size_t)u.pn * 512); }
; template <class PT, class Epi>
; __device__ __forceinline__ void gemm_phase_once(LAS unsigned char* lds, const PT& S, const Epi& E, bool epi_on) {
;     ...
;         const bool has_next = S.next(ui + 1, nxt);
;         const char* nA = has_next ? S.pa(nxt) : cA; const char* nB = has_next ? S.pb(nxt) : cB;
;         for (int t = 0; t < nt; t += 2) {
;             const bool last = (t == nt - 2);
;             const char* a1 = cA + (size_t)(t + 1) * kstep;
;             const char* a2 = last ? nA : cA + (size_t)(t + 2) * kstep; const char* b2 = last ? nB : cB + (size_t)(t + 2) * kstep;
;             const char* a3 = a2 + kstep; const char* b3 = b2 + kstep;
;     ...
; #pragma unroll
;         for (int a = 0; a < 2; ++a)
; #pragma unroll
;             for (int b = 0; b < 2; ++b)
; #pragma unroll
;                 for (int m = 0; m < 4; ++m)
; #pragma unroll
;                     for (int n = 0; n < 2; ++n) acc[a][b][m][n] = (f32x4){0.f, 0.f, 0.f, 0.f};
.LBB0_3883:
	s_ashr_i32 s11, s10, 31
	v_cmp_lt_i64_e32 vcc, s[12:13], v[144:145]
	s_lshl_b64 s[12:13], s[10:11], 20
	s_add_u32 s12, s72, s12
	s_addc_u32 s13, s73, s13
	s_and_b64 s[14:15], vcc, exec
	s_cselect_b32 s11, s13, s19
	s_cselect_b32 s39, s12, s18
	s_ashr_i32 s9, s8, 31
	s_lshl_b64 s[14:15], s[8:9], 20
	s_add_u32 s14, s84, s14
	s_addc_u32 s15, s85, s15
	s_and_b64 s[22:23], vcc, exec
	s_cselect_b32 s9, s15, s21
	s_cselect_b32 s40, s14, s20
	s_add_u32 s18, s18, 0x80080
	s_addc_u32 s19, s19, 0
	s_add_u32 s41, s20, 0x100
	v_mov_b32_e32 v4, 0
	v_mov_b32_e32 v5, 0
	v_mov_b32_e32 v6, 0
	v_mov_b32_e32 v7, 0
	s_nop 1
	v_mfma_f32_16x16x32_bf16 v[8:11], v[4:7], v[4:7], 0
	v_mfma_f32_16x16x32_bf16 v[12:15], v[4:7], v[4:7], 0
	v_mfma_f32_16x16x32_bf16 v[16:19], v[4:7], v[4:7], 0
	v_mfma_f32_32x32x16_bf16 v[20:35], v[4:7], v[4:7], 0
	v_mfma_f32_32x32x16_bf16 v[36:51], v[4:7], v[4:7], 0
	v_mfma_f32_32x32x16_bf16 v[52:67], v[4:7], v[4:7], 0
	v_mfma_f32_32x32x16_bf16 v[68:83], v[4:7], v[4:7], 0
	v_mfma_f32_32x32x16_bf16 v[84:99], v[4:7], v[4:7], 0
	v_mfma_f32_32x32x16_bf16 v[100:115], v[4:7], v[4:7], 0
	v_mfma_f32_32x32x16_bf16 v[116:131], v[4:7], v[4:7], 0
	s_addc_u32 s42, s21, 0
	s_mov_b32 s43, -2
	s_waitcnt lgkmcnt(0)
	s_waitcnt vmcnt(0)
	.p2align 6

;     __device__ __forceinline__ const char* pa(const Unit& u) const { return (const char*)(A + (size_t)u.pm * a_tile_stride + (size_t)((u.pn >> a_group_shift) * a_group_cols)); }
;     __device__ __forceinline__ const char* pb(const Unit& u) const { return (const char*)(Bt + (size_t)u.pn * b_tile_stride); }
;     __device__ __forceinline__ const char* pa(const Unit& u) const { return (const char*)(A + (size_t)u.pm * a_tile_stride + (size_t)u.pn * 512); }
; template <class PT, class Epi>
; __device__ __forceinline__ void gemm_phase_once(LAS unsigned char* lds, const PT& S, const Epi& E, bool epi_on) {
;     ...
;         const bool has_next = S.next(ui + 1, nxt);
;         const char* nA = has_next ? S.pa(nxt) : cA; const char* nB = has_next ? S.pb(nxt) : cB;
;         for (int t = 0; t < nt; t += 2) {
;             const bool last = (t == nt - 2);
;             const char* a1 = cA + (size_t)(t + 1) * kstep;
;             const char* a2 = last ? nA : cA + (size_t)(t + 2) * kstep; const char* b2 = last ? nB : cB + (size_t)(t + 2) * kstep;
;             const char* a3 = a2 + kstep; const char* b3 = b2 + kstep;
;     ...
; #pragma unroll
;         for (int a = 0; a < 2; ++a)
; #pragma unroll
;             for (int b = 0; b < 2; ++b)
; #pragma unroll
;                 for (int m = 0; m < 4; ++m)
; #pragma unroll
;                     for (int n = 0; n < 2; ++n) acc[a][b][m][n] = (f32x4){0.f, 0.f, 0.f, 0.f};
.LBB0_3906:
	s_ashr_i32 s13, s12, 31
	v_cmp_lt_i64_e64 s[24:25], s[14:15], 16
	s_lshl_b64 s[14:15], s[12:13], 20
	s_add_u32 s14, s81, s14
	s_addc_u32 s15, s96, s15
	s_and_b64 s[16:17], s[24:25], exec
	s_cselect_b32 s1, s15, s21
	s_cselect_b32 s13, s14, s20
	s_ashr_i32 s11, s10, 31
	s_lshl_b64 s[16:17], s[10:11], 20
	s_add_u32 s16, s82, s16
	s_addc_u32 s17, s83, s17
	s_and_b64 s[24:25], s[24:25], exec
	s_cselect_b32 s11, s17, s23
	s_cselect_b32 s19, s16, s22
	s_add_u32 s20, s20, 0x80080
	s_addc_u32 s21, s21, 0
	s_add_u32 s45, s22, 0x100
	v_mov_b32_e32 v4, 0
	v_mov_b32_e32 v5, 0
	v_mov_b32_e32 v6, 0
	v_mov_b32_e32 v7, 0
	s_nop 1
	v_mfma_f32_16x16x32_bf16 v[8:11], v[4:7], v[4:7], 0
	v_mfma_f32_16x16x32_bf16 v[12:15], v[4:7], v[4:7], 0
	v_mfma_f32_16x16x32_bf16 v[16:19], v[4:7], v[4:7], 0
	v_mfma_f32_32x32x16_bf16 v[20:35], v[4:7], v[4:7], 0
	v_mfma_f32_32x32x16_bf16 v[36:51], v[4:7], v[4:7], 0
	v_mfma_f32_32x32x16_bf16 v[52:67], v[4:7], v[4:7], 0
	v_mfma_f32_32x32x16_bf16 v[68:83], v[4:7], v[4:7], 0
	v_mfma_f32_32x32x16_bf16 v[84:99], v[4:7], v[4:7], 0
	v_mfma_f32_32x32x16_bf16 v[100:115], v[4:7], v[4:7], 0
	v_mfma_f32_32x32x16_bf16 v[116:131], v[4:7], v[4:7], 0
	s_addc_u32 s46, s23, 0
	s_mov_b32 s47, -2
	s_waitcnt lgkmcnt(0)
	.p2align 6

;     __device__ __forceinline__ const char* pa(const Unit& u) const { return (const char*)(A + (size_t)u.pm * a_tile_stride + (size_t)((u.pn >> a_group_shift) * a_group_cols)); }
;     __device__ __forceinline__ const char* pb(const Unit& u) const { return (const char*)(Bt + (size_t)u.pn * b_tile_stride); }
;     __device__ __forceinline__ const char* pa(const Unit& u) const { return (const char*)(A + (size_t)u.pm * a_tile_stride + (size_t)u.pn * 512); }
; template <class PT, class Epi>
; __device__ __forceinline__ void gemm_phase_once(LAS unsigned char* lds, const PT& S, const Epi& E, bool epi_on) {
;     ...
;         const bool has_next = S.next(ui + 1, nxt);
;         const char* nA = has_next ? S.pa(nxt) : cA; const char* nB = has_next ? S.pb(nxt) : cB;
;         for (int t = 0; t < nt; t += 2) {
;             const bool last = (t == nt - 2);
;             const char* a1 = cA + (size_t)(t + 1) * kstep;
;             const char* a2 = last ? nA : cA + (size_t)(t + 2) * kstep; const char* b2 = last ? nB : cB + (size_t)(t + 2) * kstep;
;             const char* a3 = a2 + kstep; const char* b3 = b2 + kstep;
;     ...
; #pragma unroll
;         for (int a = 0; a < 2; ++a)
; #pragma unroll
;             for (int b = 0; b < 2; ++b)
; #pragma unroll
;                 for (int m = 0; m < 4; ++m)
; #pragma unroll
;                     for (int n = 0; n < 2; ++n) acc[a][b][m][n] = (f32x4){0.f, 0.f, 0.f, 0.f};
.LBB0_4222:
	s_ashr_i32 s13, s12, 31
	v_cmp_lt_i64_e32 vcc, s[14:15], v[144:145]
	s_lshl_b64 s[14:15], s[12:13], 18
	v_readlane_b32 s16, v254, 48
	v_readlane_b32 s17, v254, 49
	s_add_u32 s14, s16, s14
	s_addc_u32 s15, s17, s15
	s_and_b64 s[16:17], vcc, exec
	s_cselect_b32 s13, s15, s19
	s_cselect_b32 s39, s14, s18
	s_ashr_i32 s9, s8, 31
	s_lshl_b64 s[16:17], s[8:9], 18
	v_readlane_b32 s22, v254, 7
	v_readlane_b32 s23, v254, 8
	s_add_u32 s16, s22, s16
	s_addc_u32 s17, s23, s17
	s_and_b64 s[22:23], vcc, exec
	s_cselect_b32 s9, s17, s21
	s_cselect_b32 s40, s16, s20
	s_add_u32 s18, s18, 0x20080
	s_addc_u32 s19, s19, 0
	s_add_u32 s41, s20, 0x100
	v_mov_b32_e32 v4, 0
	v_mov_b32_e32 v5, 0
	v_mov_b32_e32 v6, 0
	v_mov_b32_e32 v7, 0
	s_nop 1
	v_mfma_f32_16x16x32_bf16 v[8:11], v[4:7], v[4:7], 0
	v_mfma_f32_16x16x32_bf16 v[12:15], v[4:7], v[4:7], 0
	v_mfma_f32_16x16x32_bf16 v[16:19], v[4:7], v[4:7], 0
	v_mfma_f32_32x32x16_bf16 v[20:35], v[4:7], v[4:7], 0
	v_mfma_f32_32x32x16_bf16 v[36:51], v[4:7], v[4:7], 0
	v_mfma_f32_32x32x16_bf16 v[52:67], v[4:7], v[4:7], 0
	v_mfma_f32_32x32x16_bf16 v[68:83], v[4:7], v[4:7], 0
	v_mfma_f32_32x32x16_bf16 v[84:99], v[4:7], v[4:7], 0
	v_mfma_f32_32x32x16_bf16 v[100:115], v[4:7], v[4:7], 0
	v_mfma_f32_32x32x16_bf16 v[116:131], v[4:7], v[4:7], 0
	s_addc_u32 s42, s21, 0
	s_mov_b32 s43, -2
	s_waitcnt lgkmcnt(0)
	.p2align 6

;     __device__ __forceinline__ const char* pa(const Unit& u) const { return (const char*)(A + (size_t)u.pm * a_tile_stride + (size_t)((u.pn >> a_group_shift) * a_group_cols)); }
;     __device__ __forceinline__ const char* pb(const Unit& u) const { return (const char*)(Bt + (size_t)u.pn * b_tile_stride); }
;     __device__ __forceinline__ const char* pa(const Unit& u) const { return (const char*)(A + (size_t)u.pm * a_tile_stride + (size_t)u.pn * 512); }
; template <class PT, class Epi>
; __device__ __forceinline__ void gemm_phase_once(LAS unsigned char* lds, const PT& S, const Epi& E, bool epi_on) {
;     ...
;         const bool has_next = S.next(ui + 1, nxt);
;         const char* nA = has_next ? S.pa(nxt) : cA; const char* nB = has_next ? S.pb(nxt) : cB;
;         for (int t = 0; t < nt; t += 2) {
;             const bool last = (t == nt - 2);
;             const char* a1 = cA + (size_t)(t + 1) * kstep;
;             const char* a2 = last ? nA : cA + (size_t)(t + 2) * kstep; const char* b2 = last ? nB : cB + (size_t)(t + 2) * kstep;
;             const char* a3 = a2 + kstep; const char* b3 = b2 + kstep;
;     ...
; #pragma unroll
;         for (int a = 0; a < 2; ++a)
; #pragma unroll
;             for (int b = 0; b < 2; ++b)
; #pragma unroll
;                 for (int m = 0; m < 4; ++m)
; #pragma unroll
;                     for (int n = 0; n < 2; ++n) acc[a][b][m][n] = (f32x4){0.f, 0.f, 0.f, 0.f};
.LBB0_4349:
	s_ashr_i32 s27, s26, 31
	v_cmp_lt_i64_e32 vcc, s[28:29], v[154:155]
	s_lshl_b64 s[28:29], s[26:27], 20
	s_add_u32 s28, s72, s28
	s_addc_u32 s29, s73, s29
	s_and_b64 s[30:31], vcc, exec
	s_cselect_b32 s27, s29, s37
	s_cselect_b32 s35, s28, s36
	s_ashr_i32 s25, s24, 31
	s_lshl_b64 s[30:31], s[24:25], 20
	s_add_u32 s30, s76, s30
	s_addc_u32 s31, s77, s31
	s_and_b64 s[40:41], vcc, exec
	s_cselect_b32 s25, s31, s39
	s_cselect_b32 s62, s30, s38
	s_add_u32 s63, s38, 0x100
	v_mov_b32_e32 v4, 0
	v_mov_b32_e32 v5, 0
	v_mov_b32_e32 v6, 0
	v_mov_b32_e32 v7, 0
	s_nop 1
	v_mfma_f32_16x16x32_bf16 v[8:11], v[4:7], v[4:7], 0
	v_mfma_f32_16x16x32_bf16 v[12:15], v[4:7], v[4:7], 0
	v_mfma_f32_16x16x32_bf16 v[16:19], v[4:7], v[4:7], 0
	v_mfma_f32_32x32x16_bf16 v[20:35], v[4:7], v[4:7], 0
	v_mfma_f32_32x32x16_bf16 v[44:59], v[4:7], v[4:7], 0
	v_mfma_f32_32x32x16_bf16 v[60:75], v[4:7], v[4:7], 0
	v_mfma_f32_32x32x16_bf16 v[76:91], v[4:7], v[4:7], 0
	v_mfma_f32_32x32x16_bf16 v[92:107], v[4:7], v[4:7], 0
	v_mfma_f32_32x32x16_bf16 v[108:123], v[4:7], v[4:7], 0
	v_mfma_f32_32x32x16_bf16 v[124:139], v[4:7], v[4:7], 0
	s_addc_u32 s64, s39, 0
	s_mov_b32 s65, -2
	s_waitcnt lgkmcnt(0)
	s_waitcnt vmcnt(0)
	.p2align 6

;     __device__ __forceinline__ const char* pa(const Unit& u) const { return (const char*)(A + (size_t)u.pm * a_tile_stride + (size_t)((u.pn >> a_group_shift) * a_group_cols)); }
;     __device__ __forceinline__ const char* pb(const Unit& u) const { return (const char*)(Bt + (size_t)u.pn * b_tile_stride); }
;     __device__ __forceinline__ const char* pa(const Unit& u) const { return (const char*)(A + (size_t)u.pm * a_tile_stride + (size_t)u.pn * 512); }
; template <class PT, class Epi>
; __device__ __forceinline__ void gemm_phase_once(LAS unsigned char* lds, const PT& S, const Epi& E, bool epi_on) {
;     ...
;         const bool has_next = S.next(ui + 1, nxt);
;         const char* nA = has_next ? S.pa(nxt) : cA; const char* nB = has_next ? S.pb(nxt) : cB;
;         for (int t = 0; t < nt; t += 2) {
;             const bool last = (t == nt - 2);
;             const char* a1 = cA + (size_t)(t + 1) * kstep;
;             const char* a2 = last ? nA : cA + (size_t)(t + 2) * kstep; const char* b2 = last ? nB : cB + (size_t)(t + 2) * kstep;
;             const char* a3 = a2 + kstep; const char* b3 = b2 + kstep;
;     ...
; #pragma unroll
;         for (int a = 0; a < 2; ++a)
; #pragma unroll
;             for (int b = 0; b < 2; ++b)
; #pragma unroll
;                 for (int m = 0; m < 4; ++m)
; #pragma unroll
;                     for (int n = 0; n < 2; ++n) acc[a][b][m][n] = (f32x4){0.f, 0.f, 0.f, 0.f};
.LBB0_4817:
	s_xor_b64 s[0:1], s[14:15], -1
	s_mov_b64 s[18:19], s[6:7]
	s_and_b64 s[6:7], s[14:15], exec
	s_mov_b64 s[16:17], s[8:9]
	s_cselect_b32 s8, s28, s28
	s_cselect_b32 s6, s29, s29
	s_ashr_i32 s9, s8, 31
	s_lshl_b64 s[8:9], s[8:9], 20
	s_add_u32 s8, s72, s8
	s_addc_u32 s9, s73, s9
	s_and_b64 s[36:37], s[14:15], exec
	s_cselect_b32 s13, s9, s17
	s_cselect_b32 s35, s8, s16
	s_ashr_i32 s7, s6, 31
	s_lshl_b64 s[6:7], s[6:7], 20
	v_readlane_b32 s36, v254, 5
	v_readlane_b32 s37, v254, 6
	s_add_u32 s6, s36, s6
	s_addc_u32 s7, s37, s7
	s_and_b64 s[14:15], s[14:15], exec
	s_cselect_b32 s36, s7, s19
	s_cselect_b32 s37, s6, s18
	s_add_u32 s14, s16, 0x80080
	s_addc_u32 s15, s17, 0
	s_add_u32 s38, s18, 0x100
	v_mov_b32_e32 v4, 0
	v_mov_b32_e32 v5, 0
	v_mov_b32_e32 v6, 0
	v_mov_b32_e32 v7, 0
	s_nop 1
	v_mfma_f32_16x16x32_bf16 v[8:11], v[4:7], v[4:7], 0
	v_mfma_f32_16x16x32_bf16 v[12:15], v[4:7], v[4:7], 0
	v_mfma_f32_16x16x32_bf16 v[16:19], v[4:7], v[4:7], 0
	v_mfma_f32_32x32x16_bf16 v[20:35], v[4:7], v[4:7], 0
	v_mfma_f32_32x32x16_bf16 v[36:51], v[4:7], v[4:7], 0
	v_mfma_f32_32x32x16_bf16 v[52:67], v[4:7], v[4:7], 0
	v_mfma_f32_32x32x16_bf16 v[68:83], v[4:7], v[4:7], 0
	v_mfma_f32_32x32x16_bf16 v[84:99], v[4:7], v[4:7], 0
	v_mfma_f32_32x32x16_bf16 v[100:115], v[4:7], v[4:7], 0
	v_mfma_f32_32x32x16_bf16 v[116:131], v[4:7], v[4:7], 0
	s_addc_u32 s39, s19, 0
	s_mov_b32 s40, -2
	s_waitcnt lgkmcnt(0)
	s_waitcnt vmcnt(0)
	.p2align 6

;     __device__ __forceinline__ const char* pa(const Unit& u) const { return (const char*)(A + (size_t)u.pm * a_tile_stride + (size_t)u.pn * 512); }
;     __device__ __forceinline__ const char* pa(const Unit& u) const { return (const char*)(A + (size_t)u.pm * a_tile_stride + (size_t)((u.pn >> a_group_shift) * a_group_cols)); }
;     __device__ __forceinline__ const char* pb(const Unit& u) const { return (const char*)(Bt + (size_t)u.pn * b_tile_stride); }
; template <class PT, class Epi>
; __device__ __forceinline__ void gemm_phase_once(LAS unsigned char* lds, const PT& S, const Epi& E, bool epi_on) {
;     ...
;         const bool has_next = S.next(ui + 1, nxt);
;         const char* nA = has_next ? S.pa(nxt) : cA; const char* nB = has_next ? S.pb(nxt) : cB;
;         for (int t = 0; t < nt; t += 2) {
;             const bool last = (t == nt - 2);
;             const char* a1 = cA + (size_t)(t + 1) * kstep;
;             const char* a2 = last ? nA : cA + (size_t)(t + 2) * kstep; const char* b2 = last ? nB : cB + (size_t)(t + 2) * kstep;
;             const char* a3 = a2 + kstep; const char* b3 = b2 + kstep;
.LBB0_5017:
	s_ashr_i32 s13, s12, 31
	v_cmp_lt_i64_e32 vcc, s[14:15], v[152:153]
	s_lshl_b64 s[14:15], s[12:13], 20
	s_add_u32 s11, s2, s14
	s_addc_u32 s13, s3, s15
	s_lshl_b32 s14, s10, 8
	s_and_b32 s14, s14, 0xfffffe00
	s_ashr_i32 s15, s14, 31
	s_lshl_b64 s[14:15], s[14:15], 1
	s_add_u32 s14, s11, s14
	s_addc_u32 s15, s13, s15
	s_and_b64 s[16:17], vcc, exec
	s_cselect_b32 s13, s15, s21
	s_cselect_b32 s41, s14, s20
	s_ashr_i32 s11, s10, 31
	s_lshl_b64 s[16:17], s[10:11], 18
	v_readlane_b32 s24, v254, 52
	v_readlane_b32 s25, v254, 53
	s_add_u32 s16, s24, s16
	s_addc_u32 s17, s25, s17
	s_and_b64 s[24:25], vcc, exec
	s_cselect_b32 s11, s17, s23
	s_cselect_b32 s42, s16, s22
	s_add_u32 s20, s20, 0x80080
	s_addc_u32 s21, s21, 0
	s_add_u32 s43, s22, 0x100
	v_mov_b32_e32 v4, 0
	v_mov_b32_e32 v5, 0
	v_mov_b32_e32 v6, 0
	v_mov_b32_e32 v7, 0
	s_nop 1
	v_mfma_f32_16x16x32_bf16 v[8:11], v[4:7], v[4:7], 0
	v_mfma_f32_16x16x32_bf16 v[12:15], v[4:7], v[4:7], 0
	v_mfma_f32_16x16x32_bf16 v[16:19], v[4:7], v[4:7], 0
	v_mfma_f32_32x32x16_bf16 v[20:35], v[4:7], v[4:7], 0
	v_mfma_f32_32x32x16_bf16 v[36:51], v[4:7], v[4:7], 0
	v_mfma_f32_32x32x16_bf16 v[52:67], v[4:7], v[4:7], 0
	v_mfma_f32_32x32x16_bf16 v[76:91], v[4:7], v[4:7], 0
	v_mfma_f32_32x32x16_bf16 v[92:107], v[4:7], v[4:7], 0
	v_mfma_f32_32x32x16_bf16 v[108:123], v[4:7], v[4:7], 0
	v_mfma_f32_32x32x16_bf16 v[124:139], v[4:7], v[4:7], 0
	s_addc_u32 s44, s23, 0
	s_mov_b32 s45, -2
	s_waitcnt lgkmcnt(0)
	s_waitcnt vmcnt(0)
	.p2align 6

;     __device__ __forceinline__ const char* pa(const Unit& u) const { return (const char*)(A + (size_t)u.pm * a_tile_stride + (size_t)((u.pn >> a_group_shift) * a_group_cols)); }
;     __device__ __forceinline__ const char* pb(const Unit& u) const { return (const char*)(Bt + (size_t)u.pn * b_tile_stride); }
;     __device__ __forceinline__ const char* pa(const Unit& u) const { return (const char*)(A + (size_t)u.pm * a_tile_stride + (size_t)u.pn * 512); }
; template <class PT, class Epi>
; __device__ __forceinline__ void gemm_phase_once(LAS unsigned char* lds, const PT& S, const Epi& E, bool epi_on) {
;     ...
;         const bool has_next = S.next(ui + 1, nxt);
;         const char* nA = has_next ? S.pa(nxt) : cA; const char* nB = has_next ? S.pb(nxt) : cB;
;         for (int t = 0; t < nt; t += 2) {
;             const bool last = (t == nt - 2);
;             const char* a1 = cA + (size_t)(t + 1) * kstep;
;             const char* a2 = last ? nA : cA + (size_t)(t + 2) * kstep; const char* b2 = last ? nB : cB + (size_t)(t + 2) * kstep;
;             const char* a3 = a2 + kstep; const char* b3 = b2 + kstep;
;     ...
; #pragma unroll
;         for (int a = 0; a < 2; ++a)
; #pragma unroll
;             for (int b = 0; b < 2; ++b)
; #pragma unroll
;                 for (int m = 0; m < 4; ++m)
; #pragma unroll
;                     for (int n = 0; n < 2; ++n) acc[a][b][m][n] = (f32x4){0.f, 0.f, 0.f, 0.f};
.LBB0_5092:
	s_ashr_i32 s11, s10, 31
	v_cmp_lt_i64_e32 vcc, s[12:13], v[144:145]
	s_lshl_b64 s[12:13], s[10:11], 20
	s_add_u32 s12, s78, s12
	s_addc_u32 s13, s79, s13
	s_and_b64 s[14:15], vcc, exec
	s_cselect_b32 s11, s13, s19
	s_cselect_b32 s39, s12, s18
	s_ashr_i32 s9, s8, 31
	s_lshl_b64 s[14:15], s[8:9], 20
	s_add_u32 s14, s92, s14
	s_addc_u32 s15, s93, s15
	s_and_b64 s[22:23], vcc, exec
	s_cselect_b32 s9, s15, s21
	s_cselect_b32 s40, s14, s20
	s_add_u32 s18, s18, 0x80080
	s_addc_u32 s19, s19, 0
	s_add_u32 s41, s20, 0x100
	v_mov_b32_e32 v4, 0
	v_mov_b32_e32 v5, 0
	v_mov_b32_e32 v6, 0
	v_mov_b32_e32 v7, 0
	s_nop 1
	v_mfma_f32_16x16x32_bf16 v[8:11], v[4:7], v[4:7], 0
	v_mfma_f32_16x16x32_bf16 v[12:15], v[4:7], v[4:7], 0
	v_mfma_f32_16x16x32_bf16 v[16:19], v[4:7], v[4:7], 0
	v_mfma_f32_32x32x16_bf16 v[20:35], v[4:7], v[4:7], 0
	v_mfma_f32_32x32x16_bf16 v[36:51], v[4:7], v[4:7], 0
	v_mfma_f32_32x32x16_bf16 v[52:67], v[4:7], v[4:7], 0
	v_mfma_f32_32x32x16_bf16 v[68:83], v[4:7], v[4:7], 0
	v_mfma_f32_32x32x16_bf16 v[84:99], v[4:7], v[4:7], 0
	v_mfma_f32_32x32x16_bf16 v[100:115], v[4:7], v[4:7], 0
	v_mfma_f32_32x32x16_bf16 v[116:131], v[4:7], v[4:7], 0
	s_addc_u32 s42, s21, 0
	s_mov_b32 s43, -2
	s_waitcnt lgkmcnt(0)
	.p2align 6

;     __device__ __forceinline__ const char* pa(const Unit& u) const { return (const char*)(A + (size_t)u.pm * a_tile_stride + (size_t)((u.pn >> a_group_shift) * a_group_cols)); }
;     __device__ __forceinline__ const char* pb(const Unit& u) const { return (const char*)(Bt + (size_t)u.pn * b_tile_stride); }
;     __device__ __forceinline__ const char* pa(const Unit& u) const { return (const char*)(A + (size_t)u.pm * a_tile_stride + (size_t)u.pn * 512); }
; template <class PT, class Epi>
; __device__ __forceinline__ void gemm_phase_once(LAS unsigned char* lds, const PT& S, const Epi& E, bool epi_on) {
;     ...
;         const bool has_next = S.next(ui + 1, nxt);
;         const char* nA = has_next ? S.pa(nxt) : cA; const char* nB = has_next ? S.pb(nxt) : cB;
;         for (int t = 0; t < nt; t += 2) {
;             const bool last = (t == nt - 2);
;             const char* a1 = cA + (size_t)(t + 1) * kstep;
;             const char* a2 = last ? nA : cA + (size_t)(t + 2) * kstep; const char* b2 = last ? nB : cB + (size_t)(t + 2) * kstep;
;             const char* a3 = a2 + kstep; const char* b3 = b2 + kstep;
;     ...
; #pragma unroll
;         for (int a = 0; a < 2; ++a)
; #pragma unroll
;             for (int b = 0; b < 2; ++b)
; #pragma unroll
;                 for (int m = 0; m < 4; ++m)
; #pragma unroll
;                     for (int n = 0; n < 2; ++n) acc[a][b][m][n] = (f32x4){0.f, 0.f, 0.f, 0.f};
.LBB0_5226:
	s_ashr_i32 s11, s10, 31
	v_cmp_lt_i64_e32 vcc, s[12:13], v[144:145]
	s_lshl_b64 s[12:13], s[10:11], 20
	s_add_u32 s12, s72, s12
	s_addc_u32 s13, s73, s13
	s_and_b64 s[14:15], vcc, exec
	s_cselect_b32 s11, s13, s19
	s_cselect_b32 s40, s12, s18
	s_ashr_i32 s9, s8, 31
	s_lshl_b64 s[14:15], s[8:9], 20
	s_add_u32 s14, s84, s14
	s_addc_u32 s15, s85, s15
	s_and_b64 s[22:23], vcc, exec
	s_cselect_b32 s9, s15, s21
	s_cselect_b32 s41, s14, s20
	s_add_u32 s18, s18, 0x80080
	s_addc_u32 s19, s19, 0
	s_add_u32 s42, s20, 0x100
	v_mov_b32_e32 v4, 0
	v_mov_b32_e32 v5, 0
	v_mov_b32_e32 v6, 0
	v_mov_b32_e32 v7, 0
	s_nop 1
	v_mfma_f32_16x16x32_bf16 v[8:11], v[4:7], v[4:7], 0
	v_mfma_f32_16x16x32_bf16 v[12:15], v[4:7], v[4:7], 0
	v_mfma_f32_16x16x32_bf16 v[16:19], v[4:7], v[4:7], 0
	v_mfma_f32_32x32x16_bf16 v[20:35], v[4:7], v[4:7], 0
	v_mfma_f32_32x32x16_bf16 v[36:51], v[4:7], v[4:7], 0
	v_mfma_f32_32x32x16_bf16 v[52:67], v[4:7], v[4:7], 0
	v_mfma_f32_32x32x16_bf16 v[68:83], v[4:7], v[4:7], 0
	v_mfma_f32_32x32x16_bf16 v[84:99], v[4:7], v[4:7], 0
	v_mfma_f32_32x32x16_bf16 v[100:115], v[4:7], v[4:7], 0
	v_mfma_f32_32x32x16_bf16 v[116:131], v[4:7], v[4:7], 0
	s_addc_u32 s43, s21, 0
	s_mov_b32 s44, -2
	s_waitcnt lgkmcnt(0)
	s_waitcnt vmcnt(0)
	.p2align 6

;     __device__ __forceinline__ const char* pa(const Unit& u) const { return (const char*)(A + (size_t)u.pm * a_tile_stride + (size_t)((u.pn >> a_group_shift) * a_group_cols)); }
;     __device__ __forceinline__ const char* pb(const Unit& u) const { return (const char*)(Bt + (size_t)u.pn * b_tile_stride); }
;     __device__ __forceinline__ const char* pa(const Unit& u) const { return (const char*)(A + (size_t)u.pm * a_tile_stride + (size_t)u.pn * 512); }
; template <class PT, class Epi>
; __device__ __forceinline__ void gemm_phase_once(LAS unsigned char* lds, const PT& S, const Epi& E, bool epi_on) {
;     ...
;         const bool has_next = S.next(ui + 1, nxt);
;         const char* nA = has_next ? S.pa(nxt) : cA; const char* nB = has_next ? S.pb(nxt) : cB;
;         for (int t = 0; t < nt; t += 2) {
;             const bool last = (t == nt - 2);
;             const char* a1 = cA + (size_t)(t + 1) * kstep;
;             const char* a2 = last ? nA : cA + (size_t)(t + 2) * kstep; const char* b2 = last ? nB : cB + (size_t)(t + 2) * kstep;
;             const char* a3 = a2 + kstep; const char* b3 = b2 + kstep;
;     ...
; #pragma unroll
;         for (int a = 0; a < 2; ++a)
; #pragma unroll
;             for (int b = 0; b < 2; ++b)
; #pragma unroll
;                 for (int m = 0; m < 4; ++m)
; #pragma unroll
;                     for (int n = 0; n < 2; ++n) acc[a][b][m][n] = (f32x4){0.f, 0.f, 0.f, 0.f};
.LBB0_5455:
	s_ashr_i32 s19, s18, 31
	v_cmp_lt_i64_e32 vcc, s[20:21], v[142:143]
	s_lshl_b64 s[20:21], s[18:19], 18
	v_readlane_b32 s22, v254, 48
	v_readlane_b32 s23, v254, 49
	s_add_u32 s20, s22, s20
	s_addc_u32 s21, s23, s21
	s_and_b64 s[22:23], vcc, exec
	s_cselect_b32 s19, s21, s27
	s_cselect_b32 s51, s20, s26
	s_ashr_i32 s17, s16, 31
	s_lshl_b64 s[22:23], s[16:17], 18
	v_readlane_b32 s30, v254, 7
	v_readlane_b32 s31, v254, 8
	s_add_u32 s22, s30, s22
	s_addc_u32 s23, s31, s23
	s_and_b64 s[30:31], vcc, exec
	s_cselect_b32 s17, s23, s29
	s_cselect_b32 s52, s22, s28
	s_add_u32 s26, s26, 0x20080
	s_addc_u32 s27, s27, 0
	s_add_u32 s53, s28, 0x100
	v_mov_b32_e32 v2, 0
	v_mov_b32_e32 v3, 0
	v_mov_b32_e32 v4, 0
	v_mov_b32_e32 v5, 0
	s_nop 1
	v_mfma_f32_16x16x32_bf16 v[6:9], v[2:5], v[2:5], 0
	v_mfma_f32_16x16x32_bf16 v[10:13], v[2:5], v[2:5], 0
	v_mfma_f32_16x16x32_bf16 v[14:17], v[2:5], v[2:5], 0
	v_mfma_f32_32x32x16_bf16 v[18:33], v[2:5], v[2:5], 0
	v_mfma_f32_32x32x16_bf16 v[34:49], v[2:5], v[2:5], 0
	v_mfma_f32_32x32x16_bf16 v[50:65], v[2:5], v[2:5], 0
	v_mfma_f32_32x32x16_bf16 v[66:81], v[2:5], v[2:5], 0
	v_mfma_f32_32x32x16_bf16 v[82:97], v[2:5], v[2:5], 0
	v_mfma_f32_32x32x16_bf16 v[98:113], v[2:5], v[2:5], 0
	v_mfma_f32_32x32x16_bf16 v[114:129], v[2:5], v[2:5], 0
	s_addc_u32 s54, s29, 0
	s_mov_b32 s55, -2
	s_waitcnt lgkmcnt(0)
	.p2align 6

;     __device__ __forceinline__ const char* pa(const Unit& u) const { return (const char*)(A + (size_t)u.pm * a_tile_stride + (size_t)((u.pn >> a_group_shift) * a_group_cols)); }
;     __device__ __forceinline__ const char* pb(const Unit& u) const { return (const char*)(Bt + (size_t)u.pn * b_tile_stride); }
;     __device__ __forceinline__ const char* pa(const Unit& u) const { return (const char*)(A + (size_t)u.pm * a_tile_stride + (size_t)u.pn * 512); }
; template <class PT, class Epi>
; __device__ __forceinline__ void gemm_phase_once(LAS unsigned char* lds, const PT& S, const Epi& E, bool epi_on) {
;     ...
;         const bool has_next = S.next(ui + 1, nxt);
;         const char* nA = has_next ? S.pa(nxt) : cA; const char* nB = has_next ? S.pb(nxt) : cB;
;         for (int t = 0; t < nt; t += 2) {
;             const bool last = (t == nt - 2);
;             const char* a1 = cA + (size_t)(t + 1) * kstep;
;             const char* a2 = last ? nA : cA + (size_t)(t + 2) * kstep; const char* b2 = last ? nB : cB + (size_t)(t + 2) * kstep;
;             const char* a3 = a2 + kstep; const char* b3 = b2 + kstep;
;     ...
; #pragma unroll
;         for (int a = 0; a < 2; ++a)
; #pragma unroll
;             for (int b = 0; b < 2; ++b)
; #pragma unroll
;                 for (int m = 0; m < 4; ++m)
; #pragma unroll
;                     for (int n = 0; n < 2; ++n) acc[a][b][m][n] = (f32x4){0.f, 0.f, 0.f, 0.f};
.LBB0_5582:
	s_ashr_i32 s27, s26, 31
	v_cmp_lt_i64_e32 vcc, s[28:29], v[152:153]
	s_lshl_b64 s[28:29], s[26:27], 20
	s_add_u32 s28, s72, s28
	s_addc_u32 s29, s73, s29
	s_and_b64 s[30:31], vcc, exec
	s_cselect_b32 s27, s29, s37
	s_cselect_b32 s35, s28, s36
	s_ashr_i32 s25, s24, 31
	s_lshl_b64 s[30:31], s[24:25], 20
	s_add_u32 s30, s76, s30
	s_addc_u32 s31, s77, s31
	s_and_b64 s[40:41], vcc, exec
	s_cselect_b32 s25, s31, s39
	s_cselect_b32 s62, s30, s38
	s_add_u32 s63, s38, 0x100
	v_mov_b32_e32 v2, 0
	v_mov_b32_e32 v3, 0
	v_mov_b32_e32 v4, 0
	v_mov_b32_e32 v5, 0
	s_nop 1
	v_mfma_f32_16x16x32_bf16 v[6:9], v[2:5], v[2:5], 0
	v_mfma_f32_16x16x32_bf16 v[10:13], v[2:5], v[2:5], 0
	v_mfma_f32_16x16x32_bf16 v[14:17], v[2:5], v[2:5], 0
	v_mfma_f32_32x32x16_bf16 v[18:33], v[2:5], v[2:5], 0
	v_mfma_f32_32x32x16_bf16 v[34:49], v[2:5], v[2:5], 0
	v_mfma_f32_16x16x32_bf16 v[50:53], v[2:5], v[2:5], 0
	v_mfma_f32_16x16x32_bf16 v[54:57], v[2:5], v[2:5], 0
	v_mfma_f32_16x16x32_bf16 v[62:65], v[2:5], v[2:5], 0
	v_mfma_f32_16x16x32_bf16 v[66:69], v[2:5], v[2:5], 0
	v_mfma_f32_32x32x16_bf16 v[74:89], v[2:5], v[2:5], 0
	v_mfma_f32_32x32x16_bf16 v[90:105], v[2:5], v[2:5], 0
	v_mfma_f32_32x32x16_bf16 v[106:121], v[2:5], v[2:5], 0
	v_mfma_f32_32x32x16_bf16 v[122:137], v[2:5], v[2:5], 0
	s_addc_u32 s64, s39, 0
	s_mov_b32 s65, -2
	s_waitcnt vmcnt(0)
	s_waitcnt lgkmcnt(0)
	.p2align 6

;     __device__ __forceinline__ const char* pa(const Unit& u) const { return (const char*)(A + (size_t)u.pm * a_tile_stride + (size_t)((u.pn >> a_group_shift) * a_group_cols)); }
;     __device__ __forceinline__ const char* pb(const Unit& u) const { return (const char*)(Bt + (size_t)u.pn * b_tile_stride); }
;     __device__ __forceinline__ const char* pa(const Unit& u) const { return (const char*)(A + (size_t)u.pm * a_tile_stride + (size_t)u.pn * 512); }
; template <class PT, class Epi>
; __device__ __forceinline__ void gemm_phase_once(LAS unsigned char* lds, const PT& S, const Epi& E, bool epi_on) {
;     ...
;         const bool has_next = S.next(ui + 1, nxt);
;         const char* nA = has_next ? S.pa(nxt) : cA; const char* nB = has_next ? S.pb(nxt) : cB;
;         for (int t = 0; t < nt; t += 2) {
;             const bool last = (t == nt - 2);
;             const char* a1 = cA + (size_t)(t + 1) * kstep;
;             const char* a2 = last ? nA : cA + (size_t)(t + 2) * kstep; const char* b2 = last ? nB : cB + (size_t)(t + 2) * kstep;
;             const char* a3 = a2 + kstep; const char* b3 = b2 + kstep;
;     ...
; #pragma unroll
;         for (int a = 0; a < 2; ++a)
; #pragma unroll
;             for (int b = 0; b < 2; ++b)
; #pragma unroll
;                 for (int m = 0; m < 4; ++m)
; #pragma unroll
;                     for (int n = 0; n < 2; ++n) acc[a][b][m][n] = (f32x4){0.f, 0.f, 0.f, 0.f};
.LBB0_5741:
	s_add_u32 s18, s18, 0x160080
	s_addc_u32 s19, s19, 0
	s_add_u32 s47, s20, 0x100
	v_mov_b32_e32 v0, 0
	v_mov_b32_e32 v1, 0
	v_mov_b32_e32 v2, 0
	v_mov_b32_e32 v3, 0
	s_nop 1
	v_mfma_f32_16x16x32_bf16 v[4:7], v[0:3], v[0:3], 0
	v_mfma_f32_16x16x32_bf16 v[8:11], v[0:3], v[0:3], 0
	v_mfma_f32_16x16x32_bf16 v[12:15], v[0:3], v[0:3], 0
	v_mfma_f32_32x32x16_bf16 v[16:31], v[0:3], v[0:3], 0
	v_mfma_f32_32x32x16_bf16 v[32:47], v[0:3], v[0:3], 0
	v_mfma_f32_32x32x16_bf16 v[48:63], v[0:3], v[0:3], 0
	v_mfma_f32_32x32x16_bf16 v[64:79], v[0:3], v[0:3], 0
	v_mfma_f32_32x32x16_bf16 v[80:95], v[0:3], v[0:3], 0
	v_mfma_f32_32x32x16_bf16 v[96:111], v[0:3], v[0:3], 0
	v_mfma_f32_32x32x16_bf16 v[112:127], v[0:3], v[0:3], 0
	s_addc_u32 s48, s21, 0
	s_mov_b32 s49, -2
	s_waitcnt lgkmcnt(0)
	.p2align 6
